# gates sigmoid via v_rcp_f32 (dead IEEE-division VALU removed) + FFN-in DPP zero-init removal + epilogue load hoists
# speedup vs baseline: 1.0116x; 1.0116x over previous
.LBB0_1485:
	v_lshl_or_b32 v150, s33, 8, v155
	v_ashrrev_i32_e32 v151, 31, v150
	v_lshl_add_u32 v148, s30, 8, v1
	v_lshl_add_u64 v[178:179], v[150:151], 2, s[8:9]
	s_nop 15
	s_nop 15
	v_cvt_f32_i32 v126, v126
	v_cvt_f32_i32 v127, v127
	v_cvt_f32_i32 v128, v128
	v_cvt_f32_i32 v129, v129
	v_cvt_f32_i32 v114, v114
	v_cvt_f32_i32 v115, v115
	v_cvt_f32_i32 v116, v116
	v_cvt_f32_i32 v117, v117
	v_cvt_f32_i32 v122, v122
	v_cvt_f32_i32 v123, v123
	v_cvt_f32_i32 v124, v124
	v_cvt_f32_i32 v125, v125
	v_cvt_f32_i32 v106, v106
	v_cvt_f32_i32 v107, v107
	v_cvt_f32_i32 v108, v108
	v_cvt_f32_i32 v109, v109
	v_cvt_f32_i32 v118, v118
	v_cvt_f32_i32 v119, v119
	v_cvt_f32_i32 v120, v120
	v_cvt_f32_i32 v121, v121
	v_cvt_f32_i32 v102, v102
	v_cvt_f32_i32 v103, v103
	v_cvt_f32_i32 v104, v104
	v_cvt_f32_i32 v105, v105
	v_cvt_f32_i32 v110, v110
	v_cvt_f32_i32 v111, v111
	v_cvt_f32_i32 v112, v112
	v_cvt_f32_i32 v113, v113
	v_cvt_f32_i32 v98, v98
	v_cvt_f32_i32 v99, v99
	v_cvt_f32_i32 v100, v100
	v_cvt_f32_i32 v101, v101
	v_cvt_f32_i32 v86, v86
	v_cvt_f32_i32 v87, v87
	v_cvt_f32_i32 v88, v88
	v_cvt_f32_i32 v89, v89
	v_cvt_f32_i32 v46, v46
	v_cvt_f32_i32 v47, v47
	v_cvt_f32_i32 v48, v48
	v_cvt_f32_i32 v49, v49
	v_cvt_f32_i32 v70, v70
	v_cvt_f32_i32 v71, v71
	v_cvt_f32_i32 v72, v72
	v_cvt_f32_i32 v73, v73
	v_cvt_f32_i32 v42, v42
	v_cvt_f32_i32 v43, v43
	v_cvt_f32_i32 v44, v44
	v_cvt_f32_i32 v45, v45
	v_cvt_f32_i32 v62, v62
	v_cvt_f32_i32 v63, v63
	v_cvt_f32_i32 v64, v64
	v_cvt_f32_i32 v65, v65
	v_cvt_f32_i32 v34, v34
	v_cvt_f32_i32 v35, v35
	v_cvt_f32_i32 v36, v36
	v_cvt_f32_i32 v37, v37
	v_cvt_f32_i32 v54, v54
	v_cvt_f32_i32 v55, v55
	v_cvt_f32_i32 v56, v56
	v_cvt_f32_i32 v57, v57
	v_cvt_f32_i32 v26, v26
	v_cvt_f32_i32 v27, v27
	v_cvt_f32_i32 v28, v28
	v_cvt_f32_i32 v29, v29
	v_cvt_f32_i32 v94, v94
	v_cvt_f32_i32 v95, v95
	v_cvt_f32_i32 v96, v96
	v_cvt_f32_i32 v97, v97
	v_cvt_f32_i32 v78, v78
	v_cvt_f32_i32 v79, v79
	v_cvt_f32_i32 v80, v80
	v_cvt_f32_i32 v81, v81
	v_cvt_f32_i32 v90, v90
	v_cvt_f32_i32 v91, v91
	v_cvt_f32_i32 v92, v92
	v_cvt_f32_i32 v93, v93
	v_cvt_f32_i32 v66, v66
	v_cvt_f32_i32 v67, v67
	v_cvt_f32_i32 v68, v68
	v_cvt_f32_i32 v69, v69
	v_cvt_f32_i32 v82, v82
	v_cvt_f32_i32 v83, v83
	v_cvt_f32_i32 v84, v84
	v_cvt_f32_i32 v85, v85
	v_cvt_f32_i32 v58, v58
	v_cvt_f32_i32 v59, v59
	v_cvt_f32_i32 v60, v60
	v_cvt_f32_i32 v61, v61
	v_cvt_f32_i32 v74, v74
	v_cvt_f32_i32 v75, v75
	v_cvt_f32_i32 v76, v76
	v_cvt_f32_i32 v77, v77
	v_cvt_f32_i32 v50, v50
	v_cvt_f32_i32 v51, v51
	v_cvt_f32_i32 v52, v52
	v_cvt_f32_i32 v53, v53
	v_cvt_f32_i32 v38, v38
	v_cvt_f32_i32 v39, v39
	v_cvt_f32_i32 v40, v40
	v_cvt_f32_i32 v41, v41
	v_cvt_f32_i32 v14, v14
	v_cvt_f32_i32 v15, v15
	v_cvt_f32_i32 v16, v16
	v_cvt_f32_i32 v17, v17
	v_cvt_f32_i32 v30, v30
	v_cvt_f32_i32 v31, v31
	v_cvt_f32_i32 v32, v32
	v_cvt_f32_i32 v33, v33
	v_cvt_f32_i32 v10, v10
	v_cvt_f32_i32 v11, v11
	v_cvt_f32_i32 v12, v12
	v_cvt_f32_i32 v13, v13
	v_cvt_f32_i32 v22, v22
	v_cvt_f32_i32 v23, v23
	v_cvt_f32_i32 v24, v24
	v_cvt_f32_i32 v25, v25
	v_cvt_f32_i32 v6, v6
	v_cvt_f32_i32 v7, v7
	v_cvt_f32_i32 v8, v8
	v_cvt_f32_i32 v9, v9
	v_cvt_f32_i32 v18, v18
	v_cvt_f32_i32 v19, v19
	v_cvt_f32_i32 v20, v20
	v_cvt_f32_i32 v21, v21
	v_cvt_f32_i32 v2, v2
	v_cvt_f32_i32 v3, v3
	v_cvt_f32_i32 v4, v4
	v_cvt_f32_i32 v5, v5
	global_load_dwordx4 v[166:169], v[178:179], off
	v_ashrrev_i32_e32 v149, 31, v148
	v_lshl_add_u64 v[164:165], v[148:149], 2, s[6:7]
	global_load_dword v152, v[164:165], off
	global_load_dword v154, v[164:165], off offset:64
	global_load_dword v156, v[164:165], off offset:128
	v_add_u32_e32 v146, 0x80, v148
	v_ashrrev_i32_e32 v147, 31, v146
	v_lshl_add_u64 v[170:171], v[146:147], 2, s[6:7]
	global_load_dword v158, v[164:165], off offset:192
	global_load_dword v160, v[164:165], off offset:576
	global_load_dword v162, v[164:165], off offset:640
	s_nop 0
	global_load_dword v164, v[164:165], off offset:704
	s_nop 0
	global_load_dword v182, v[170:171], off
	s_nop 0
	global_load_dwordx4 v[170:173], v[178:179], off offset:16
	global_load_dwordx4 v[174:177], v[178:179], off offset:512
	s_nop 0
	global_load_dwordx4 v[178:181], v[178:179], off offset:528
	s_waitcnt vmcnt(0)
	v_pk_mul_f32 v[184:185], v[166:167], v[152:153] op_sel_hi:[1,0]
	s_nop 0
	v_pk_mul_f32 v[184:185], v[126:127], v[184:185]
	v_pk_mul_f32 v[126:127], v[166:167], v[154:155] op_sel_hi:[1,0]
	v_pk_mul_f32 v[186:187], v[168:169], v[152:153] op_sel_hi:[1,0]
	v_pk_mul_f32 v[122:123], v[122:123], v[126:127]
	v_pk_mul_f32 v[126:127], v[166:167], v[156:157] op_sel_hi:[1,0]
	v_pk_mul_f32 v[128:129], v[128:129], v[186:187]
	v_pk_mul_f32 v[118:119], v[118:119], v[126:127]
	v_pk_mul_f32 v[126:127], v[166:167], v[158:159] op_sel_hi:[1,0]
	v_pk_mul_f32 v[186:187], v[168:169], v[154:155] op_sel_hi:[1,0]
	v_pk_mul_f32 v[110:111], v[110:111], v[126:127]
	v_pk_mul_f32 v[126:127], v[166:167], v[182:183] op_sel_hi:[1,0]
	v_pk_mul_f32 v[124:125], v[124:125], v[186:187]
	v_pk_mul_f32 v[94:95], v[94:95], v[126:127]
	v_pk_mul_f32 v[126:127], v[166:167], v[160:161] op_sel_hi:[1,0]
	v_pk_mul_f32 v[186:187], v[168:169], v[156:157] op_sel_hi:[1,0]
	v_pk_mul_f32 v[90:91], v[90:91], v[126:127]
	v_pk_mul_f32 v[126:127], v[166:167], v[162:163] op_sel_hi:[1,0]
	v_pk_mul_f32 v[120:121], v[120:121], v[186:187]
	v_pk_mul_f32 v[82:83], v[82:83], v[126:127]
	v_pk_mul_f32 v[126:127], v[166:167], v[164:165] op_sel_hi:[1,0]
	v_pk_mul_f32 v[166:167], v[168:169], v[164:165] op_sel_hi:[1,0]
	v_pk_mul_f32 v[74:75], v[74:75], v[126:127]
	v_pk_mul_f32 v[76:77], v[76:77], v[166:167]
	v_pk_mul_f32 v[126:127], v[152:153], v[170:171] op_sel_hi:[0,1]
	v_pk_mul_f32 v[166:167], v[152:153], v[172:173] op_sel_hi:[0,1]
	v_pk_mul_f32 v[116:117], v[116:117], v[166:167]
	v_pk_mul_f32 v[166:167], v[114:115], v[126:127]
	v_pk_mul_f32 v[114:115], v[154:155], v[170:171] op_sel_hi:[0,1]
	v_pk_mul_f32 v[126:127], v[154:155], v[172:173] op_sel_hi:[0,1]
	v_pk_mul_f32 v[108:109], v[108:109], v[126:127]
	v_pk_mul_f32 v[106:107], v[106:107], v[114:115]
	v_pk_mul_f32 v[114:115], v[156:157], v[170:171] op_sel_hi:[0,1]
	v_pk_mul_f32 v[126:127], v[156:157], v[172:173] op_sel_hi:[0,1]
	v_pk_mul_f32 v[104:105], v[104:105], v[126:127]
	v_pk_mul_f32 v[102:103], v[102:103], v[114:115]
	v_pk_mul_f32 v[114:115], v[158:159], v[170:171] op_sel_hi:[0,1]
	v_pk_mul_f32 v[126:127], v[158:159], v[172:173] op_sel_hi:[0,1]
	v_pk_mul_f32 v[100:101], v[100:101], v[126:127]
	v_pk_mul_f32 v[98:99], v[98:99], v[114:115]
	v_pk_mul_f32 v[114:115], v[182:183], v[170:171] op_sel_hi:[0,1]
	v_pk_mul_f32 v[126:127], v[182:183], v[172:173] op_sel_hi:[0,1]
	v_pk_mul_f32 v[80:81], v[80:81], v[126:127]
	v_pk_mul_f32 v[78:79], v[78:79], v[114:115]
	v_pk_mul_f32 v[114:115], v[160:161], v[170:171] op_sel_hi:[0,1]
	v_pk_mul_f32 v[126:127], v[160:161], v[172:173] op_sel_hi:[0,1]
	v_pk_mul_f32 v[68:69], v[68:69], v[126:127]
	v_pk_mul_f32 v[66:67], v[66:67], v[114:115]
	v_pk_mul_f32 v[114:115], v[170:171], v[162:163] op_sel_hi:[1,0]
	v_pk_mul_f32 v[126:127], v[172:173], v[162:163] op_sel_hi:[1,0]
	v_pk_mul_f32 v[58:59], v[58:59], v[114:115]
	v_pk_mul_f32 v[60:61], v[60:61], v[126:127]
	v_pk_mul_f32 v[114:115], v[170:171], v[164:165] op_sel_hi:[1,0]
	v_pk_mul_f32 v[126:127], v[172:173], v[164:165] op_sel_hi:[1,0]
	v_pk_mul_f32 v[50:51], v[50:51], v[114:115]
	v_pk_mul_f32 v[52:53], v[52:53], v[126:127]
	v_pk_mul_f32 v[114:115], v[152:153], v[174:175] op_sel_hi:[0,1]
	v_pk_mul_f32 v[126:127], v[152:153], v[176:177] op_sel_hi:[0,1]
	v_pk_mul_f32 v[88:89], v[88:89], v[126:127]
	v_pk_mul_f32 v[114:115], v[86:87], v[114:115]
	v_pk_mul_f32 v[86:87], v[154:155], v[174:175] op_sel_hi:[0,1]
	v_pk_mul_f32 v[126:127], v[154:155], v[176:177] op_sel_hi:[0,1]
	v_pk_mul_f32 v[72:73], v[72:73], v[126:127]
	v_pk_mul_f32 v[70:71], v[70:71], v[86:87]
	v_pk_mul_f32 v[86:87], v[156:157], v[174:175] op_sel_hi:[0,1]
	v_pk_mul_f32 v[126:127], v[156:157], v[176:177] op_sel_hi:[0,1]
	v_pk_mul_f32 v[64:65], v[64:65], v[126:127]
	v_pk_mul_f32 v[62:63], v[62:63], v[86:87]
	v_pk_mul_f32 v[86:87], v[158:159], v[174:175] op_sel_hi:[0,1]
	v_pk_mul_f32 v[126:127], v[158:159], v[176:177] op_sel_hi:[0,1]
	v_pk_mul_f32 v[56:57], v[56:57], v[126:127]
	v_pk_mul_f32 v[54:55], v[54:55], v[86:87]
	v_pk_mul_f32 v[86:87], v[182:183], v[174:175] op_sel_hi:[0,1]
	v_pk_mul_f32 v[126:127], v[182:183], v[176:177] op_sel_hi:[0,1]
	v_pk_mul_f32 v[40:41], v[40:41], v[126:127]
	v_pk_mul_f32 v[38:39], v[38:39], v[86:87]
	v_pk_mul_f32 v[86:87], v[160:161], v[174:175] op_sel_hi:[0,1]
	v_pk_mul_f32 v[126:127], v[160:161], v[176:177] op_sel_hi:[0,1]
	v_pk_mul_f32 v[32:33], v[32:33], v[126:127]
	v_pk_mul_f32 v[30:31], v[30:31], v[86:87]
	v_pk_mul_f32 v[86:87], v[162:163], v[174:175] op_sel_hi:[0,1]
	v_pk_mul_f32 v[126:127], v[162:163], v[176:177] op_sel_hi:[0,1]
	v_pk_mul_f32 v[24:25], v[24:25], v[126:127]
	v_pk_mul_f32 v[22:23], v[22:23], v[86:87]
	v_pk_mul_f32 v[86:87], v[174:175], v[164:165] op_sel_hi:[1,0]
	v_pk_mul_f32 v[126:127], v[176:177], v[164:165] op_sel_hi:[1,0]
	v_pk_mul_f32 v[18:19], v[18:19], v[86:87]
	v_pk_mul_f32 v[20:21], v[20:21], v[126:127]
	v_pk_mul_f32 v[126:127], v[152:153], v[178:179] op_sel_hi:[0,1]
	v_pk_mul_f32 v[86:87], v[152:153], v[180:181] op_sel_hi:[0,1]
	v_pk_mul_f32 v[86:87], v[48:49], v[86:87]
	v_pk_mul_f32 v[126:127], v[46:47], v[126:127]
	v_pk_mul_f32 v[48:49], v[154:155], v[178:179] op_sel_hi:[0,1]
	v_pk_mul_f32 v[46:47], v[154:155], v[180:181] op_sel_hi:[0,1]
	v_pk_mul_f32 v[46:47], v[44:45], v[46:47]
	v_pk_mul_f32 v[48:49], v[42:43], v[48:49]
	v_pk_mul_f32 v[44:45], v[156:157], v[178:179] op_sel_hi:[0,1]
	v_pk_mul_f32 v[42:43], v[156:157], v[180:181] op_sel_hi:[0,1]
	v_pk_mul_f32 v[42:43], v[36:37], v[42:43]
	v_pk_mul_f32 v[44:45], v[34:35], v[44:45]
	v_pk_mul_f32 v[34:35], v[158:159], v[178:179] op_sel_hi:[0,1]
	v_pk_mul_f32 v[36:37], v[158:159], v[180:181] op_sel_hi:[0,1]
	v_mul_f32_e32 v152, 0xbfb8aa3b, v184
	v_pk_mul_f32 v[28:29], v[28:29], v[36:37]
	v_pk_mul_f32 v[36:37], v[26:27], v[34:35]
	v_pk_mul_f32 v[26:27], v[182:183], v[178:179] op_sel_hi:[0,1]
	v_exp_f32_e32 v152, v152
	v_pk_mul_f32 v[26:27], v[14:15], v[26:27]
	v_pk_mul_f32 v[14:15], v[160:161], v[178:179] op_sel_hi:[0,1]
	v_pk_mul_f32 v[14:15], v[10:11], v[14:15]
	v_pk_mul_f32 v[10:11], v[162:163], v[178:179] op_sel_hi:[0,1]
	v_pk_mul_f32 v[10:11], v[6:7], v[10:11]
	v_pk_mul_f32 v[6:7], v[164:165], v[178:179] op_sel_hi:[0,1]
	v_pk_mul_f32 v[2:3], v[2:3], v[6:7]
	v_lshlrev_b64 v[6:7], 14, v[148:149]
	v_add_f32_e32 v149, 1.0, v152
	v_pk_mul_f32 v[34:35], v[182:183], v[180:181] op_sel_hi:[0,1]
	v_pk_mul_f32 v[16:17], v[16:17], v[34:35]
	v_pk_mul_f32 v[34:35], v[160:161], v[180:181] op_sel_hi:[0,1]
	v_pk_mul_f32 v[12:13], v[12:13], v[34:35]
	v_pk_mul_f32 v[34:35], v[162:163], v[180:181] op_sel_hi:[0,1]
	v_pk_mul_f32 v[8:9], v[8:9], v[34:35]
	v_pk_mul_f32 v[34:35], v[164:165], v[180:181] op_sel_hi:[0,1]
	v_pk_mul_f32 v[4:5], v[4:5], v[34:35]
	v_lshlrev_b64 v[34:35], 1, v[150:151]
	v_mul_f32_e32 v156, 0xbfb8aa3b, v166
	v_exp_f32_e32 v156, v156
	v_pk_mul_f32 v[186:187], v[168:169], v[158:159] op_sel_hi:[1,0]
	v_add_f32_e32 v152, 1.0, v156
	v_mul_f32_e32 v154, 0xbfb8aa3b, v185
	v_rcp_f32_e32 v149, v149
	v_exp_f32_e32 v154, v154
	v_pk_mul_f32 v[112:113], v[112:113], v[186:187]
	v_pk_mul_f32 v[186:187], v[168:169], v[182:183] op_sel_hi:[1,0]
	v_pk_mul_f32 v[96:97], v[96:97], v[186:187]
	v_pk_mul_f32 v[186:187], v[168:169], v[160:161] op_sel_hi:[1,0]
	v_add_f32_e32 v154, 1.0, v154
	v_mul_f32_e32 v158, 0xbfb8aa3b, v167
	v_exp_f32_e32 v158, v158
	v_rcp_f32_e32 v150, v152
	v_pk_mul_f32 v[92:93], v[92:93], v[186:187]
	v_pk_mul_f32 v[186:187], v[168:169], v[162:163] op_sel_hi:[1,0]
	v_add_f32_e32 v156, 1.0, v158
	v_mul_f32_e32 v128, 0xbfb8aa3b, v128
	v_exp_f32_e32 v128, v128
	v_rcp_f32_e32 v151, v154
	v_add_f32_e32 v128, 1.0, v128
	v_mul_f32_e32 v116, 0xbfb8aa3b, v116
	v_exp_f32_e32 v116, v116
	v_rcp_f32_e32 v152, v156
	v_add_f32_e32 v116, 1.0, v116
	v_mul_f32_e32 v129, 0xbfb8aa3b, v129
	v_rcp_f32_e32 v128, v128
	v_exp_f32_e32 v129, v129
	s_nop 0
	v_add_f32_e32 v129, 1.0, v129
	v_mul_f32_e32 v117, 0xbfb8aa3b, v117
	v_rcp_f32_e32 v116, v116
	v_exp_f32_e32 v117, v117
	s_nop 0
	v_add_f32_e32 v117, 1.0, v117
	v_rcp_f32_e32 v129, v129
	v_mul_f32_e32 v114, 0xbfb8aa3b, v114
	v_exp_f32_e32 v114, v114
	s_nop 0
	v_add_f32_e32 v114, 1.0, v114
	v_cvt_pk_bf16_f32 v162, v149, v151
	v_cvt_pk_bf16_f32 v163, v128, v129
	v_mul_f32_e32 v126, 0xbfb8aa3b, v126
	v_rcp_f32_e32 v117, v117
	v_cvt_pk_bf16_f32 v164, v150, v152
	v_cvt_pk_bf16_f32 v165, v116, v117
	v_exp_f32_e32 v126, v126
	s_nop 0
	v_add_f32_e32 v126, 1.0, v126
	v_mul_f32_e32 v115, 0xbfb8aa3b, v115
	v_rcp_f32_e32 v114, v114
	v_exp_f32_e32 v115, v115
	s_nop 0
	v_add_f32_e32 v115, 1.0, v115
	v_mul_f32_e32 v127, 0xbfb8aa3b, v127
	v_exp_f32_e32 v127, v127
	v_rcp_f32_e32 v116, v126
	v_add_f32_e32 v127, 1.0, v127
	v_mul_f32_e32 v88, 0xbfb8aa3b, v88
	v_rcp_f32_e32 v115, v115
	v_exp_f32_e32 v88, v88
	s_nop 0
	v_add_f32_e32 v88, 1.0, v88
	v_mul_f32_e32 v86, 0xbfb8aa3b, v86
	v_exp_f32_e32 v86, v86
	v_rcp_f32_e32 v117, v127
	v_add_f32_e32 v86, 1.0, v86
	v_mul_f32_e32 v89, 0xbfb8aa3b, v89
	v_rcp_f32_e32 v88, v88
	v_exp_f32_e32 v89, v89
	s_nop 0
	v_add_f32_e32 v89, 1.0, v89
	v_mul_f32_e32 v87, 0xbfb8aa3b, v87
	v_rcp_f32_e32 v126, v86
	v_exp_f32_e32 v87, v87
	s_nop 0
	v_add_f32_e32 v87, 1.0, v87
	v_div_scale_f32 v128, s[34:35], v87, v87, 1.0
	v_rcp_f32_e32 v149, v128
	v_rcp_f32_e32 v89, v89
	v_lshl_add_u64 v[6:7], s[10:11], 0, v[6:7]
	v_fma_f32 v86, -v128, v149, 1.0
	v_fmac_f32_e32 v149, v86, v149
	v_lshl_add_u64 v[6:7], v[6:7], 0, v[34:35]
	global_store_dwordx4 v[6:7], v[162:165], off
	v_rcp_f32_e32 v127, v87
	v_cvt_pk_bf16_f32 v86, v114, v115
	v_mul_f32_e32 v114, 0xbfb8aa3b, v122
	v_exp_f32_e32 v114, v114
	v_cvt_pk_bf16_f32 v87, v88, v89
	v_cvt_pk_bf16_f32 v88, v116, v117
	v_cvt_pk_bf16_f32 v89, v126, v127
	global_store_dwordx4 v[6:7], v[86:89], off offset:256
	v_mul_f32_e32 v106, 0xbfb8aa3b, v106
	v_exp_f32_e32 v106, v106
	v_add_f32_e32 v88, 1.0, v114
	v_add_f32_e32 v106, 1.0, v106
	v_mul_f32_e32 v107, 0xbfb8aa3b, v107
	v_exp_f32_e32 v107, v107
	v_rcp_f32_e32 v88, v88
	v_mul_f32_e32 v116, 0xbfb8aa3b, v123
	v_exp_f32_e32 v116, v116
	s_nop 0
	v_add_f32_e32 v115, 1.0, v116
	v_rcp_f32_e32 v89, v106
	v_add_f32_e32 v107, 1.0, v107
	v_mul_f32_e32 v122, 0xbfb8aa3b, v124
	v_exp_f32_e32 v122, v122
	v_rcp_f32_e32 v106, v115
	v_add_f32_e32 v116, 1.0, v122
	v_mul_f32_e32 v108, 0xbfb8aa3b, v108
	v_exp_f32_e32 v108, v108
	v_rcp_f32_e32 v114, v107
	v_add_f32_e32 v108, 1.0, v108
	v_mul_f32_e32 v123, 0xbfb8aa3b, v125
	v_exp_f32_e32 v123, v123
	v_rcp_f32_e32 v107, v116
	v_add_f32_e32 v117, 1.0, v123
	v_mul_f32_e32 v109, 0xbfb8aa3b, v109
	v_exp_f32_e32 v109, v109
	v_rcp_f32_e32 v115, v108
	v_add_f32_e32 v109, 1.0, v109
	v_mul_f32_e32 v70, 0xbfb8aa3b, v70
	v_exp_f32_e32 v70, v70
	v_rcp_f32_e32 v108, v117
	v_add_f32_e32 v70, 1.0, v70
	v_cvt_pk_bf16_f32 v106, v88, v106
	v_rcp_f32_e32 v109, v109
	v_or_b32_e32 v86, 16, v148
	v_ashrrev_i32_e32 v87, 31, v86
	v_lshlrev_b64 v[86:87], 14, v[86:87]
	v_mul_f32_e32 v48, 0xbfb8aa3b, v48
	v_lshl_add_u64 v[86:87], s[10:11], 0, v[86:87]
	v_cvt_pk_bf16_f32 v107, v107, v108
	v_cvt_pk_bf16_f32 v108, v89, v114
	v_exp_f32_e32 v48, v48
	v_lshl_add_u64 v[86:87], v[86:87], 0, v[34:35]
	v_cvt_pk_bf16_f32 v109, v115, v109
	global_store_dwordx4 v[86:87], v[106:109], off
	v_add_f32_e32 v48, 1.0, v48
	v_mul_f32_e32 v71, 0xbfb8aa3b, v71
	v_rcp_f32_e32 v70, v70
	v_exp_f32_e32 v71, v71
	s_nop 0
	v_add_f32_e32 v71, 1.0, v71
	v_mul_f32_e32 v49, 0xbfb8aa3b, v49
	v_rcp_f32_e32 v48, v48
	v_exp_f32_e32 v49, v49
	s_nop 0
	v_add_f32_e32 v49, 1.0, v49
	v_mul_f32_e32 v72, 0xbfb8aa3b, v72
	v_rcp_f32_e32 v71, v71
	v_exp_f32_e32 v72, v72
	s_nop 0
	v_add_f32_e32 v72, 1.0, v72
	v_mul_f32_e32 v46, 0xbfb8aa3b, v46
	v_rcp_f32_e32 v49, v49
	v_exp_f32_e32 v46, v46
	s_nop 0
	v_add_f32_e32 v46, 1.0, v46
	v_mul_f32_e32 v73, 0xbfb8aa3b, v73
	v_rcp_f32_e32 v72, v72
	v_exp_f32_e32 v73, v73
	s_nop 0
	v_add_f32_e32 v73, 1.0, v73
	v_mul_f32_e32 v47, 0xbfb8aa3b, v47
	v_rcp_f32_e32 v88, v46
	v_exp_f32_e32 v47, v47
	s_nop 0
	v_add_f32_e32 v47, 1.0, v47
	v_rcp_f32_e32 v73, v73
	v_mul_f32_e32 v62, 0xbfb8aa3b, v62
	v_rcp_f32_e32 v89, v47
	v_cvt_pk_bf16_f32 v46, v70, v71
	v_mul_f32_e32 v70, 0xbfb8aa3b, v118
	v_exp_f32_e32 v70, v70
	v_cvt_pk_bf16_f32 v47, v72, v73
	v_cvt_pk_bf16_f32 v48, v48, v49
	v_cvt_pk_bf16_f32 v49, v88, v89
	global_store_dwordx4 v[86:87], v[46:49], off offset:256
	v_mul_f32_e32 v73, 0xbfb8aa3b, v102
	v_exp_f32_e32 v73, v73
	v_add_f32_e32 v48, 1.0, v70
	v_exp_f32_e32 v62, v62
	v_or_b32_e32 v46, 32, v148
	v_ashrrev_i32_e32 v47, 31, v46
	v_add_f32_e32 v71, 1.0, v73
	v_mul_f32_e32 v72, 0xbfb8aa3b, v119
	v_rcp_f32_e32 v48, v48
	v_exp_f32_e32 v72, v72
	s_nop 0
	v_add_f32_e32 v72, 1.0, v72
	v_mul_f32_e32 v86, 0xbfb8aa3b, v103
	v_exp_f32_e32 v86, v86
	v_rcp_f32_e32 v49, v71
	v_add_f32_e32 v73, 1.0, v86
	v_mul_f32_e32 v87, 0xbfb8aa3b, v120
	v_exp_f32_e32 v87, v87
	v_rcp_f32_e32 v70, v72
	v_add_f32_e32 v86, 1.0, v87
	v_rcp_f32_e32 v72, v73
	v_mul_f32_e32 v88, 0xbfb8aa3b, v104
	v_exp_f32_e32 v88, v88
	s_nop 0
	v_add_f32_e32 v87, 1.0, v88
	v_mul_f32_e32 v89, 0xbfb8aa3b, v121
	v_exp_f32_e32 v89, v89
	v_rcp_f32_e32 v71, v86
	v_add_f32_e32 v88, 1.0, v89
	v_mul_f32_e32 v102, 0xbfb8aa3b, v105
	v_exp_f32_e32 v102, v102
	v_rcp_f32_e32 v73, v87
	v_add_f32_e32 v89, 1.0, v102
	v_cvt_pk_bf16_f32 v70, v48, v70
	v_add_f32_e32 v48, 1.0, v62
	v_rcp_f32_e32 v86, v88
	s_nop 0
	v_cvt_pk_bf16_f32 v71, v71, v86
	v_lshlrev_b64 v[46:47], 14, v[46:47]
	v_mul_f32_e32 v44, 0xbfb8aa3b, v44
	v_lshl_add_u64 v[46:47], s[10:11], 0, v[46:47]
	v_cvt_pk_bf16_f32 v72, v49, v72
	v_exp_f32_e32 v44, v44
	v_lshl_add_u64 v[46:47], v[46:47], 0, v[34:35]
	v_rcp_f32_e32 v87, v89
	s_nop 0
	v_cvt_pk_bf16_f32 v73, v73, v87
	global_store_dwordx4 v[46:47], v[70:73], off
	v_add_f32_e32 v44, 1.0, v44
	v_mul_f32_e32 v63, 0xbfb8aa3b, v63
	v_rcp_f32_e32 v48, v48
	v_exp_f32_e32 v63, v63
	s_nop 0
	v_add_f32_e32 v62, 1.0, v63
	v_mul_f32_e32 v45, 0xbfb8aa3b, v45
	v_rcp_f32_e32 v44, v44
	v_exp_f32_e32 v45, v45
	s_nop 0
	v_add_f32_e32 v45, 1.0, v45
	v_rcp_f32_e32 v49, v62
	v_mul_f32_e32 v64, 0xbfb8aa3b, v64
	v_exp_f32_e32 v64, v64
	s_nop 0
	v_add_f32_e32 v63, 1.0, v64
	v_mul_f32_e32 v42, 0xbfb8aa3b, v42
	v_rcp_f32_e32 v45, v45
	v_exp_f32_e32 v42, v42
	s_nop 0
	v_add_f32_e32 v42, 1.0, v42
	v_rcp_f32_e32 v62, v63
	v_mul_f32_e32 v65, 0xbfb8aa3b, v65
	v_exp_f32_e32 v65, v65
	s_nop 0
	v_add_f32_e32 v64, 1.0, v65
	v_mul_f32_e32 v43, 0xbfb8aa3b, v43
	v_rcp_f32_e32 v63, v42
	v_exp_f32_e32 v43, v43
	s_nop 0
	v_add_f32_e32 v43, 1.0, v43
	v_rcp_f32_e32 v64, v64
	v_mul_f32_e32 v54, 0xbfb8aa3b, v54
	v_rcp_f32_e32 v65, v43
	v_cvt_pk_bf16_f32 v42, v48, v49
	v_mul_f32_e32 v48, 0xbfb8aa3b, v110
	v_exp_f32_e32 v48, v48
	v_cvt_pk_bf16_f32 v43, v62, v64
	v_cvt_pk_bf16_f32 v44, v44, v45
	v_cvt_pk_bf16_f32 v45, v63, v65
	global_store_dwordx4 v[46:47], v[42:45], off offset:256
	v_mul_f32_e32 v49, 0xbfb8aa3b, v98
	v_exp_f32_e32 v49, v49
	v_add_f32_e32 v44, 1.0, v48
	v_exp_f32_e32 v54, v54
	v_or_b32_e32 v42, 48, v148
	v_ashrrev_i32_e32 v43, 31, v42
	v_add_f32_e32 v47, 1.0, v49
	v_mul_f32_e32 v48, 0xbfb8aa3b, v111
	v_rcp_f32_e32 v44, v44
	v_exp_f32_e32 v48, v48
	s_nop 0
	v_add_f32_e32 v48, 1.0, v48
	v_rcp_f32_e32 v46, v47
	v_mul_f32_e32 v62, 0xbfb8aa3b, v99
	v_exp_f32_e32 v62, v62
	s_nop 0
	v_add_f32_e32 v49, 1.0, v62
	v_mul_f32_e32 v63, 0xbfb8aa3b, v112
	v_exp_f32_e32 v63, v63
	v_rcp_f32_e32 v45, v48
	v_add_f32_e32 v62, 1.0, v63
	v_mul_f32_e32 v64, 0xbfb8aa3b, v100
	v_exp_f32_e32 v64, v64
	v_rcp_f32_e32 v47, v49
	v_add_f32_e32 v63, 1.0, v64
	v_mul_f32_e32 v65, 0xbfb8aa3b, v113
	v_exp_f32_e32 v65, v65
	v_rcp_f32_e32 v48, v62
	v_add_f32_e32 v64, 1.0, v65
	v_mul_f32_e32 v70, 0xbfb8aa3b, v101
	v_exp_f32_e32 v70, v70
	v_rcp_f32_e32 v49, v63
	v_add_f32_e32 v65, 1.0, v70
	v_rcp_f32_e32 v62, v64
	v_cvt_pk_bf16_f32 v44, v44, v45
	v_cvt_pk_bf16_f32 v45, v48, v62
	v_add_f32_e32 v48, 1.0, v54
	v_lshlrev_b64 v[42:43], 14, v[42:43]
	v_lshl_add_u64 v[42:43], s[10:11], 0, v[42:43]
	v_mul_f32_e32 v36, 0xbfb8aa3b, v36
	v_lshl_add_u64 v[42:43], v[42:43], 0, v[34:35]
	v_exp_f32_e32 v36, v36
	v_rcp_f32_e32 v63, v65
	v_cvt_pk_bf16_f32 v46, v46, v47
	v_cvt_pk_bf16_f32 v47, v49, v63
	global_store_dwordx4 v[42:43], v[44:47], off
	v_add_f32_e32 v36, 1.0, v36
	v_mul_f32_e32 v49, 0xbfb8aa3b, v55
	v_exp_f32_e32 v49, v49
	v_rcp_f32_e32 v44, v48
	v_add_f32_e32 v46, 1.0, v49
	v_mul_f32_e32 v37, 0xbfb8aa3b, v37
	v_exp_f32_e32 v37, v37
	v_rcp_f32_e32 v36, v36
	v_add_f32_e32 v37, 1.0, v37
	v_rcp_f32_e32 v45, v46
	v_mul_f32_e32 v54, 0xbfb8aa3b, v56
	v_exp_f32_e32 v54, v54
	s_nop 0
	v_add_f32_e32 v48, 1.0, v54
	v_mul_f32_e32 v28, 0xbfb8aa3b, v28
	v_exp_f32_e32 v28, v28
	v_rcp_f32_e32 v37, v37
	v_add_f32_e32 v28, 1.0, v28
	v_mul_f32_e32 v55, 0xbfb8aa3b, v57
	v_exp_f32_e32 v55, v55
	v_rcp_f32_e32 v46, v48
	v_add_f32_e32 v49, 1.0, v55
	v_mul_f32_e32 v29, 0xbfb8aa3b, v29
	v_exp_f32_e32 v29, v29
	v_rcp_f32_e32 v28, v28
	v_add_f32_e32 v29, 1.0, v29
	v_rcp_f32_e32 v47, v49
	v_cvt_pk_bf16_f32 v44, v44, v45
	v_cvt_pk_bf16_f32 v45, v46, v47
	v_mul_f32_e32 v46, 0xbfb8aa3b, v94
	v_rcp_f32_e32 v29, v29
	v_exp_f32_e32 v48, v46
	v_cvt_pk_bf16_f32 v46, v36, v37
	v_cvt_pk_bf16_f32 v47, v28, v29
	global_store_dwordx4 v[42:43], v[44:47], off offset:256
	v_add_f32_e32 v36, 1.0, v48
	v_lshlrev_b64 v[28:29], 14, v[146:147]
	v_lshl_add_u64 v[28:29], s[10:11], 0, v[28:29]
	v_lshl_add_u64 v[28:29], v[28:29], 0, v[34:35]
	v_mul_f32_e32 v43, 0xbfb8aa3b, v78
	v_exp_f32_e32 v43, v43
	s_nop 0
	v_add_f32_e32 v37, 1.0, v43
	v_mul_f32_e32 v42, 0xbfb8aa3b, v95
	v_exp_f32_e32 v42, v42
	v_rcp_f32_e32 v34, v36
	v_add_f32_e32 v42, 1.0, v42
	v_rcp_f32_e32 v36, v37
	v_mul_f32_e32 v44, 0xbfb8aa3b, v79
	v_exp_f32_e32 v44, v44
	s_nop 0
	v_add_f32_e32 v43, 1.0, v44
	v_mul_f32_e32 v45, 0xbfb8aa3b, v96
	v_exp_f32_e32 v45, v45
	v_rcp_f32_e32 v35, v42
	v_add_f32_e32 v44, 1.0, v45
	v_mul_f32_e32 v46, 0xbfb8aa3b, v80
	v_exp_f32_e32 v46, v46
	v_rcp_f32_e32 v37, v43
	v_add_f32_e32 v45, 1.0, v46
	v_mul_f32_e32 v47, 0xbfb8aa3b, v97
	v_exp_f32_e32 v47, v47
	v_rcp_f32_e32 v42, v44
	v_add_f32_e32 v46, 1.0, v47
	v_mul_f32_e32 v48, 0xbfb8aa3b, v81
	v_exp_f32_e32 v48, v48
	v_rcp_f32_e32 v43, v45
	v_add_f32_e32 v47, 1.0, v48
	v_mul_f32_e32 v38, 0xbfb8aa3b, v38
	v_exp_f32_e32 v38, v38
	s_nop 0
	v_add_f32_e32 v38, 1.0, v38
	v_rcp_f32_e32 v44, v46
	v_cvt_pk_bf16_f32 v34, v34, v35
	v_cvt_pk_bf16_f32 v35, v42, v44
	v_mul_f32_e32 v26, 0xbfb8aa3b, v26
	v_exp_f32_e32 v26, v26
	v_rcp_f32_e32 v45, v47
	v_cvt_pk_bf16_f32 v36, v36, v37
	v_cvt_pk_bf16_f32 v37, v43, v45
	global_store_dwordx4 v[28:29], v[34:37], off
	v_add_f32_e32 v26, 1.0, v26
	v_mul_f32_e32 v39, 0xbfb8aa3b, v39
	v_exp_f32_e32 v39, v39
	v_rcp_f32_e32 v34, v38
	v_add_f32_e32 v36, 1.0, v39
	v_mul_f32_e32 v27, 0xbfb8aa3b, v27
	v_exp_f32_e32 v27, v27
	v_rcp_f32_e32 v26, v26
	v_add_f32_e32 v27, 1.0, v27
	v_rcp_f32_e32 v35, v36
	v_mul_f32_e32 v40, 0xbfb8aa3b, v40
	v_exp_f32_e32 v40, v40
	s_nop 0
	v_add_f32_e32 v38, 1.0, v40
	v_mul_f32_e32 v16, 0xbfb8aa3b, v16
	v_exp_f32_e32 v16, v16
	v_rcp_f32_e32 v27, v27
	v_add_f32_e32 v16, 1.0, v16
	v_mul_f32_e32 v41, 0xbfb8aa3b, v41
	v_exp_f32_e32 v41, v41
	v_rcp_f32_e32 v36, v38
	v_add_f32_e32 v39, 1.0, v41
	v_mul_f32_e32 v17, 0xbfb8aa3b, v17
	v_exp_f32_e32 v17, v17
	v_rcp_f32_e32 v16, v16
	v_add_f32_e32 v17, 1.0, v17
	v_rcp_f32_e32 v37, v39
	v_cvt_pk_bf16_f32 v34, v34, v35
	v_rcp_f32_e32 v17, v17
	v_mul_f32_e32 v38, 0xbfb8aa3b, v90
	v_exp_f32_e32 v38, v38
	v_cvt_pk_bf16_f32 v35, v36, v37
	v_cvt_pk_bf16_f32 v36, v26, v27
	v_cvt_pk_bf16_f32 v37, v16, v17
	global_store_dwordx4 v[28:29], v[34:37], off offset:256
	v_add_f32_e32 v26, 1.0, v38
	s_nop 1
	v_mul_f32_e32 v34, 0xbfb8aa3b, v66
	v_exp_f32_e32 v34, v34
	v_mul_f32_e32 v36, 0xbfb8aa3b, v91
	v_add_f32_e32 v28, 1.0, v34
	v_rcp_f32_e32 v26, v26
	v_exp_f32_e32 v36, v36
	s_nop 0
	v_add_f32_e32 v34, 1.0, v36
	v_mul_f32_e32 v35, 0xbfb8aa3b, v67
	v_rcp_f32_e32 v28, v28
	v_exp_f32_e32 v35, v35
	s_nop 0
	v_add_f32_e32 v35, 1.0, v35
	v_mul_f32_e32 v37, 0xbfb8aa3b, v92
	v_exp_f32_e32 v37, v37
	v_rcp_f32_e32 v27, v34
	v_add_f32_e32 v36, 1.0, v37
	v_mul_f32_e32 v38, 0xbfb8aa3b, v68
	v_exp_f32_e32 v38, v38
	v_rcp_f32_e32 v29, v35
	v_add_f32_e32 v37, 1.0, v38
	v_mul_f32_e32 v39, 0xbfb8aa3b, v93
	v_exp_f32_e32 v39, v39
	v_rcp_f32_e32 v34, v36
	v_add_f32_e32 v38, 1.0, v39
	v_mul_f32_e32 v40, 0xbfb8aa3b, v69
	v_exp_f32_e32 v40, v40
	v_rcp_f32_e32 v35, v37
	v_add_f32_e32 v39, 1.0, v40
	v_cvt_pk_bf16_f32 v26, v26, v27
	v_mul_f32_e32 v27, 0xbfb8aa3b, v30
	v_rcp_f32_e32 v36, v38
	v_exp_f32_e32 v30, v27
	s_nop 0
	v_add_f32_e32 v30, 1.0, v30
	v_rcp_f32_e32 v37, v39
	v_cvt_pk_bf16_f32 v27, v34, v36
	v_cvt_pk_bf16_f32 v28, v28, v29
	v_cvt_pk_bf16_f32 v29, v35, v37
	v_add_co_u32_e32 v34, vcc, s55, v6
	v_mul_f32_e32 v14, 0xbfb8aa3b, v14
	s_nop 0
	v_addc_co_u32_e32 v35, vcc, 0, v7, vcc
	v_exp_f32_e32 v14, v14
	global_store_dwordx4 v[34:35], v[26:29], off
	v_mul_f32_e32 v31, 0xbfb8aa3b, v31
	v_exp_f32_e32 v31, v31
	v_add_f32_e32 v14, 1.0, v14
	v_rcp_f32_e32 v26, v30
	v_add_f32_e32 v28, 1.0, v31
	v_mul_f32_e32 v15, 0xbfb8aa3b, v15
	v_exp_f32_e32 v15, v15
	v_rcp_f32_e32 v14, v14
	v_add_f32_e32 v15, 1.0, v15
	v_rcp_f32_e32 v27, v28
	v_mul_f32_e32 v32, 0xbfb8aa3b, v32
	v_exp_f32_e32 v32, v32
	s_nop 0
	v_add_f32_e32 v30, 1.0, v32
	v_mul_f32_e32 v12, 0xbfb8aa3b, v12
	v_exp_f32_e32 v12, v12
	v_rcp_f32_e32 v15, v15
	v_add_f32_e32 v12, 1.0, v12
	v_mul_f32_e32 v33, 0xbfb8aa3b, v33
	v_exp_f32_e32 v33, v33
	v_rcp_f32_e32 v28, v30
	v_add_f32_e32 v31, 1.0, v33
	v_mul_f32_e32 v13, 0xbfb8aa3b, v13
	v_exp_f32_e32 v13, v13
	v_rcp_f32_e32 v29, v12
	v_add_f32_e32 v13, 1.0, v13
	v_rcp_f32_e32 v30, v31
	v_lshl_add_u64 v[16:17], v[6:7], 0, s[16:17]
	v_rcp_f32_e32 v31, v13
	v_mul_f32_e32 v12, 0xbfb8aa3b, v82
	v_exp_f32_e32 v32, v12
	v_cvt_pk_bf16_f32 v12, v26, v27
	v_cvt_pk_bf16_f32 v13, v28, v30
	v_cvt_pk_bf16_f32 v14, v14, v15
	v_cvt_pk_bf16_f32 v15, v29, v31
	global_store_dwordx4 v[16:17], v[12:15], off offset:256
	v_add_f32_e32 v26, 1.0, v32
	s_nop 1
	v_mul_f32_e32 v16, 0xbfb8aa3b, v58
	v_exp_f32_e32 v16, v16
	v_pk_mul_f32 v[84:85], v[84:85], v[186:187]
	v_add_f32_e32 v16, 1.0, v16
	v_mul_f32_e32 v28, 0xbfb8aa3b, v83
	v_exp_f32_e32 v28, v28
	v_rcp_f32_e32 v14, v26
	v_add_f32_e32 v17, 1.0, v28
	v_mul_f32_e32 v27, 0xbfb8aa3b, v59
	v_rcp_f32_e32 v16, v16
	v_exp_f32_e32 v27, v27
	s_nop 0
	v_add_f32_e32 v27, 1.0, v27
	v_rcp_f32_e32 v15, v17
	v_mul_f32_e32 v29, 0xbfb8aa3b, v84
	v_exp_f32_e32 v29, v29
	s_nop 0
	v_add_f32_e32 v28, 1.0, v29
	v_mul_f32_e32 v30, 0xbfb8aa3b, v60
	v_exp_f32_e32 v30, v30
	v_rcp_f32_e32 v17, v27
	v_add_f32_e32 v29, 1.0, v30
	v_mul_f32_e32 v31, 0xbfb8aa3b, v85
	v_exp_f32_e32 v31, v31
	v_rcp_f32_e32 v26, v28
	v_add_f32_e32 v30, 1.0, v31
	v_mul_f32_e32 v32, 0xbfb8aa3b, v61
	v_exp_f32_e32 v32, v32
	v_rcp_f32_e32 v27, v29
	v_add_f32_e32 v31, 1.0, v32
	v_cvt_pk_bf16_f32 v14, v14, v15
	v_mul_f32_e32 v15, 0xbfb8aa3b, v22
	v_rcp_f32_e32 v28, v30
	v_exp_f32_e32 v22, v15
	s_nop 0
	v_add_f32_e32 v22, 1.0, v22
	v_rcp_f32_e32 v29, v31
	v_cvt_pk_bf16_f32 v15, v26, v28
	v_cvt_pk_bf16_f32 v16, v16, v17
	v_cvt_pk_bf16_f32 v17, v27, v29
	v_add_co_u32_e32 v26, vcc, s60, v6
	v_mul_f32_e32 v10, 0xbfb8aa3b, v10
	s_nop 0
	v_addc_co_u32_e32 v27, vcc, 0, v7, vcc
	v_exp_f32_e32 v10, v10
	global_store_dwordx4 v[26:27], v[14:17], off
	v_mul_f32_e32 v23, 0xbfb8aa3b, v23
	v_exp_f32_e32 v23, v23
	v_add_f32_e32 v10, 1.0, v10
	v_rcp_f32_e32 v14, v22
	v_add_f32_e32 v16, 1.0, v23
	v_mul_f32_e32 v11, 0xbfb8aa3b, v11
	v_exp_f32_e32 v11, v11
	v_rcp_f32_e32 v10, v10
	v_add_f32_e32 v11, 1.0, v11
	v_rcp_f32_e32 v15, v16
	v_mul_f32_e32 v24, 0xbfb8aa3b, v24
	v_exp_f32_e32 v24, v24
	s_nop 0
	v_add_f32_e32 v22, 1.0, v24
	v_mul_f32_e32 v8, 0xbfb8aa3b, v8
	v_exp_f32_e32 v8, v8
	v_rcp_f32_e32 v11, v11
	v_add_f32_e32 v8, 1.0, v8
	v_mul_f32_e32 v25, 0xbfb8aa3b, v25
	v_exp_f32_e32 v25, v25
	v_rcp_f32_e32 v16, v22
	v_add_f32_e32 v23, 1.0, v25
	v_mul_f32_e32 v9, 0xbfb8aa3b, v9
	v_exp_f32_e32 v9, v9
	v_rcp_f32_e32 v17, v8
	v_add_f32_e32 v9, 1.0, v9
	v_rcp_f32_e32 v22, v23
	v_lshl_add_u64 v[12:13], v[6:7], 0, s[18:19]
	v_rcp_f32_e32 v23, v9
	v_mul_f32_e32 v8, 0xbfb8aa3b, v74
	v_exp_f32_e32 v24, v8
	v_cvt_pk_bf16_f32 v8, v14, v15
	v_cvt_pk_bf16_f32 v9, v16, v22
	v_cvt_pk_bf16_f32 v10, v10, v11
	v_cvt_pk_bf16_f32 v11, v17, v23
	global_store_dwordx4 v[12:13], v[8:11], off offset:256
	v_add_f32_e32 v14, 1.0, v24
	s_nop 1
	v_mul_f32_e32 v12, 0xbfb8aa3b, v50
	v_exp_f32_e32 v12, v12
	v_lshl_add_u64 v[8:9], v[6:7], 0, s[20:21]
	v_add_f32_e32 v12, 1.0, v12
	v_mul_f32_e32 v16, 0xbfb8aa3b, v75
	v_exp_f32_e32 v16, v16
	v_rcp_f32_e32 v10, v14
	v_add_f32_e32 v13, 1.0, v16
	v_mul_f32_e32 v15, 0xbfb8aa3b, v51
	v_rcp_f32_e32 v12, v12
	v_exp_f32_e32 v15, v15
	s_nop 0
	v_add_f32_e32 v15, 1.0, v15
	v_rcp_f32_e32 v11, v13
	v_mul_f32_e32 v17, 0xbfb8aa3b, v76
	v_exp_f32_e32 v17, v17
	s_nop 0
	v_add_f32_e32 v16, 1.0, v17
	v_mul_f32_e32 v22, 0xbfb8aa3b, v52
	v_exp_f32_e32 v22, v22
	v_rcp_f32_e32 v13, v15
	v_add_f32_e32 v17, 1.0, v22
	v_mul_f32_e32 v23, 0xbfb8aa3b, v77
	v_exp_f32_e32 v23, v23
	v_rcp_f32_e32 v14, v16
	v_add_f32_e32 v22, 1.0, v23
	v_mul_f32_e32 v24, 0xbfb8aa3b, v53
	v_exp_f32_e32 v24, v24
	v_rcp_f32_e32 v15, v17
	v_add_f32_e32 v23, 1.0, v24
	v_cvt_pk_bf16_f32 v10, v10, v11
	v_mul_f32_e32 v11, 0xbfb8aa3b, v18
	v_rcp_f32_e32 v16, v22
	v_exp_f32_e32 v18, v11
	v_cvt_pk_bf16_f32 v11, v14, v16
	v_add_f32_e32 v14, 1.0, v18
	v_rcp_f32_e32 v17, v23
	v_cvt_pk_bf16_f32 v12, v12, v13
	v_cvt_pk_bf16_f32 v13, v15, v17
	v_add_co_u32_e32 v6, vcc, s61, v6
	v_mul_f32_e32 v2, 0xbfb8aa3b, v2
	s_nop 0
	v_addc_co_u32_e32 v7, vcc, 0, v7, vcc
	v_exp_f32_e32 v2, v2
	global_store_dwordx4 v[6:7], v[10:13], off
	v_add_f32_e32 v2, 1.0, v2
	s_nop 1
	v_mul_f32_e32 v13, 0xbfb8aa3b, v19
	v_exp_f32_e32 v13, v13
	v_rcp_f32_e32 v6, v14
	v_add_f32_e32 v10, 1.0, v13
	v_mul_f32_e32 v3, 0xbfb8aa3b, v3
	v_exp_f32_e32 v3, v3
	v_rcp_f32_e32 v7, v2
	v_add_f32_e32 v3, 1.0, v3
	v_rcp_f32_e32 v2, v10
	v_mul_f32_e32 v14, 0xbfb8aa3b, v20
	v_exp_f32_e32 v14, v14
	s_nop 0
	v_add_f32_e32 v12, 1.0, v14
	v_mul_f32_e32 v4, 0xbfb8aa3b, v4
	v_exp_f32_e32 v4, v4
	v_rcp_f32_e32 v10, v3
	v_add_f32_e32 v4, 1.0, v4
	v_mul_f32_e32 v15, 0xbfb8aa3b, v21
	v_exp_f32_e32 v15, v15
	v_rcp_f32_e32 v3, v12
	v_add_f32_e32 v13, 1.0, v15
	v_mul_f32_e32 v5, 0xbfb8aa3b, v5
	v_exp_f32_e32 v5, v5
	v_rcp_f32_e32 v11, v4
	v_add_f32_e32 v5, 1.0, v5
	v_rcp_f32_e32 v4, v13
	v_cvt_pk_bf16_f32 v2, v6, v2
	v_rcp_f32_e32 v5, v5
	s_andn2_b64 vcc, exec, s[4:5]
	s_mov_b64 s[4:5], -1
	v_cvt_pk_bf16_f32 v3, v3, v4
	v_cvt_pk_bf16_f32 v4, v7, v10
	v_cvt_pk_bf16_f32 v5, v11, v5
	global_store_dwordx4 v[8:9], v[2:5], off offset:256
	s_cbranch_vccnz .LBB0_1474
	s_andn2_b64 vcc, exec, s[0:1]
	s_cbranch_vccnz .LBB0_1473
	s_barrier
	s_branch .LBB0_1473

.LBB0_1887:
	s_or_b64 exec, exec, s[42:43]
	v_lshl_or_b32 v212, s40, 7, v194
	v_ashrrev_i32_e32 v213, 31, v212
	v_lshlrev_b64 v[132:133], 2, v[212:213]
	v_lshl_add_u64 v[206:207], s[56:57], 0, v[132:133]
	v_lshl_add_u64 v[208:209], v[130:131], 2, v[196:197]
	v_add_co_u32_e32 v130, vcc, 0x15000, v206
	v_lshl_add_u64 v[210:211], s[58:59], 0, v[132:133]
	s_nop 0
	v_addc_co_u32_e32 v131, vcc, 0, v207, vcc
	v_add_co_u32_e32 v132, vcc, 0x2b000, v206
	s_waitcnt lgkmcnt(0)
	s_barrier
	v_mov_b32_e32 v140, 0
	v_addc_co_u32_e32 v133, vcc, 0, v207, vcc
	v_mov_b32_e32 v134, s94
	v_mov_b32_e32 v136, v224
	v_mov_b32_e32 v137, v225
	v_mov_b32_e32 v138, v226
	v_mov_b32_e32 v139, v227
	s_nop 0
	s_nop 0
	s_nop 0
	v_add_co_u32_e32 v130, vcc, 0xa000, v210
	v_mov_b32_e32 v146, 0
	s_nop 0
	v_addc_co_u32_e32 v131, vcc, 0, v211, vcc
	v_add_co_u32_e32 v142, vcc, 0xa000, v206
	v_mov_b32_e32 v130, v228
	v_mov_b32_e32 v131, v229
	v_mov_b32_e32 v132, v230
	v_mov_b32_e32 v133, v231
	s_nop 0
	s_nop 0
	s_nop 0
	v_addc_co_u32_e32 v143, vcc, 0, v207, vcc
	v_add_co_u32_e32 v144, vcc, 0x20000, v206
	v_mov_b32_e32 v147, 0
	s_nop 0
	v_addc_co_u32_e32 v145, vcc, 0, v207, vcc
	s_nop 0
	s_nop 0
	v_add_co_u32_e32 v142, vcc, 0x35000, v206
	v_mov_b32_e32 v144, 0
	s_nop 0
	v_addc_co_u32_e32 v143, vcc, 0, v207, vcc
	s_nop 0
	v_mov_b32_e32 v145, 0
	s_and_saveexec_b64 s[40:41], s[26:27]
	ds_read_b128 v[144:147], v215
	s_or_b64 exec, exec, s[40:41]
	v_mov_b32_e32 v141, 0
	v_mov_b32_e32 v142, 0
	v_mov_b32_e32 v143, 0
	s_and_saveexec_b64 s[40:41], s[26:27]
	ds_read_b128 v[140:143], v215 offset:512
	s_or_b64 exec, exec, s[40:41]
	s_nop 0
	v_pk_mul_f32 v[176:177], v[176:177], v[134:135] op_sel_hi:[1,0]
	v_pk_mul_f32 v[178:179], v[178:179], v[134:135] op_sel_hi:[1,0]
	v_pk_mul_f32 v[226:227], v[148:149], v[176:177]
	v_pk_mul_f32 v[230:231], v[176:177], v[156:157]
	v_pk_mul_f32 v[176:177], v[176:177], v[152:153]
	v_pk_mul_f32 v[152:153], v[134:135], v[162:163] op_sel_hi:[0,1]
	v_pk_mul_f32 v[134:135], v[134:135], v[160:161] op_sel_hi:[0,1]
	v_pk_mul_f32 v[224:225], v[150:151], v[178:179]
	v_pk_mul_f32 v[228:229], v[178:179], v[158:159]
	v_pk_mul_f32 v[178:179], v[178:179], v[154:155]
	v_pk_mul_f32 v[154:155], v[168:169], v[134:135]
	v_pk_mul_f32 v[156:157], v[134:135], v[164:165]
	v_pk_mul_f32 v[158:159], v[134:135], v[172:173]
	s_waitcnt lgkmcnt(0)
	v_mov_b32_dpp v160, v144 row_ror:1 row_mask:0xf bank_mask:0xf
	v_mov_b32_dpp v161, v144 row_ror:2 row_mask:0xf bank_mask:0xf
	v_mov_b32_dpp v168, v145 row_ror:1 row_mask:0xf bank_mask:0xf
	v_mov_b32_dpp v169, v145 row_ror:2 row_mask:0xf bank_mask:0xf
	v_mov_b32_dpp v135, v126 row_ror:1 row_mask:0xf bank_mask:0xf
	v_mov_b32_dpp v172, v126 row_ror:2 row_mask:0xf bank_mask:0xf
	v_mov_b32_dpp v238, v122 row_ror:1 row_mask:0xf bank_mask:0xf
	v_mov_b32_dpp v144, v140 row_ror:1 row_mask:0xf bank_mask:0xf
	v_mov_b32_dpp v239, v122 row_ror:2 row_mask:0xf bank_mask:0xf
	v_mov_b32_dpp v145, v140 row_ror:2 row_mask:0xf bank_mask:0xf
	v_mov_b32_dpp v223, v146 row_ror:1 row_mask:0xf bank_mask:0xf
	v_mov_b32_dpp v233, v146 row_ror:2 row_mask:0xf bank_mask:0xf
	v_mov_b32_dpp v235, v147 row_ror:1 row_mask:0xf bank_mask:0xf
	v_mov_b32_dpp v237, v147 row_ror:2 row_mask:0xf bank_mask:0xf
	v_cndmask_b32_e64 v163, v238, v144, s[8:9]
	v_cndmask_b32_e64 v162, v135, v160, s[8:9]
	v_cndmask_b32_e64 v165, v239, v145, s[6:7]
	v_cndmask_b32_e64 v164, v172, v161, s[6:7]
	v_mov_b32_e32 v160, v126
	v_mov_b32_e32 v161, v122
	v_mov_b32_e32 v144, v176
	v_mov_b32_e32 v145, v158
	v_mov_b32_e32 v146, v136
	v_mov_b32_e32 v147, v130
	v_pk_mul_f32 v[150:151], v[152:153], v[166:167]
	v_pk_fma_f32 v[166:167], v[160:161], v[144:145], v[146:147]
	v_mov_b32_e32 v160, v230
	v_mov_b32_e32 v161, v156
	v_mov_b32_dpp v176, v123 row_ror:1 row_mask:0xf bank_mask:0xf
	v_mov_b32_dpp v122, v141 row_ror:1 row_mask:0xf bank_mask:0xf
	v_pk_mul_f32 v[148:149], v[170:171], v[152:153]
	v_pk_mul_f32 v[152:153], v[152:153], v[174:175]
	v_mov_b32_dpp v173, v127 row_ror:1 row_mask:0xf bank_mask:0xf
	v_pk_fma_f32 v[166:167], v[160:161], v[162:163], v[166:167]
	v_mov_b32_e32 v162, v226
	v_mov_b32_dpp v126, v141 row_ror:2 row_mask:0xf bank_mask:0xf
	v_cndmask_b32_e64 v141, v176, v122, s[8:9]
	v_mov_b32_e32 v122, v127
	v_mov_b32_e32 v158, v177
	v_mov_b32_e32 v130, v137
	v_mov_b32_dpp v174, v127 row_ror:2 row_mask:0xf bank_mask:0xf
	v_mov_b32_e32 v163, v154
	v_mov_b32_dpp v226, v123 row_ror:2 row_mask:0xf bank_mask:0xf
	v_cndmask_b32_e64 v140, v173, v168, s[8:9]
	v_pk_fma_f32 v[122:123], v[122:123], v[158:159], v[130:131]
	v_mov_b32_e32 v156, v231
	v_pk_fma_f32 v[170:171], v[162:163], v[164:165], v[166:167]
	v_cndmask_b32_e64 v165, v226, v126, s[6:7]
	v_cndmask_b32_e64 v164, v174, v169, s[6:7]
	v_pk_fma_f32 v[122:123], v[156:157], v[140:141], v[122:123]
	v_mov_b32_e32 v154, v227
	v_mov_b32_dpp v175, v128 row_ror:1 row_mask:0xf bank_mask:0xf
	v_pk_fma_f32 v[122:123], v[154:155], v[164:165], v[122:123]
	v_mov_b32_dpp v177, v124 row_ror:1 row_mask:0xf bank_mask:0xf
	v_mov_b32_dpp v126, v142 row_ror:1 row_mask:0xf bank_mask:0xf
	v_mov_b32_e32 v166, v128
	v_mov_b32_e32 v167, v124
	v_mov_b32_e32 v140, v178
	v_mov_b32_e32 v141, v152
	v_mov_b32_e32 v164, v138
	v_mov_b32_e32 v165, v132
	v_mov_b32_dpp v232, v128 row_ror:2 row_mask:0xf bank_mask:0xf
	v_mov_b32_dpp v227, v124 row_ror:2 row_mask:0xf bank_mask:0xf
	v_mov_b32_dpp v136, v142 row_ror:2 row_mask:0xf bank_mask:0xf
	v_cndmask_b32_e64 v127, v177, v126, s[8:9]
	v_cndmask_b32_e64 v126, v175, v223, s[8:9]
	v_pk_fma_f32 v[168:169], v[166:167], v[140:141], v[164:165]
	v_mov_b32_e32 v166, v228
	v_mov_b32_e32 v167, v150
	v_cndmask_b32_e64 v137, v227, v136, s[6:7]
	v_cndmask_b32_e64 v136, v232, v233, s[6:7]
	v_pk_fma_f32 v[126:127], v[166:167], v[126:127], v[168:169]
	v_mov_b32_e32 v168, v224
	v_mov_b32_e32 v169, v148
	v_mov_b32_dpp v178, v125 row_ror:1 row_mask:0xf bank_mask:0xf
	v_mov_b32_dpp v124, v143 row_ror:1 row_mask:0xf bank_mask:0xf
	v_mov_b32_dpp v234, v129 row_ror:1 row_mask:0xf bank_mask:0xf
	v_mov_b32_dpp v236, v129 row_ror:2 row_mask:0xf bank_mask:0xf
	v_pk_fma_f32 v[126:127], v[168:169], v[136:137], v[126:127]
	v_cndmask_b32_e64 v137, v178, v124, s[8:9]
	v_mov_b32_e32 v124, v129
	v_mul_f32_e32 v129, 0xbfb8aa3b, v122
	v_mov_b32_e32 v152, v179
	v_mov_b32_e32 v132, v139
	v_exp_f32_e32 v129, v129
	v_mov_b32_dpp v223, v125 row_ror:2 row_mask:0xf bank_mask:0xf
	v_mov_b32_dpp v128, v143 row_ror:2 row_mask:0xf bank_mask:0xf
	v_cndmask_b32_e64 v136, v234, v235, s[8:9]
	v_pk_fma_f32 v[124:125], v[124:125], v[152:153], v[132:133]
	v_mov_b32_e32 v150, v229
	v_cndmask_b32_e64 v143, v223, v128, s[6:7]
	v_cndmask_b32_e64 v142, v236, v237, s[6:7]
	v_pk_fma_f32 v[124:125], v[150:151], v[136:137], v[124:125]
	v_mov_b32_e32 v148, v225
	v_pk_fma_f32 v[124:125], v[148:149], v[142:143], v[124:125]
	v_add_f32_e32 v129, 1.0, v129
	v_mul_f32_e32 v136, 0xbfb8aa3b, v126
	v_mul_f32_e32 v137, 0xbfb8aa3b, v124
	v_mul_f32_e32 v128, 0xbfb8aa3b, v170
	v_rcp_f32_e32 v129, v129
	v_exp_f32_e32 v136, v136
	v_exp_f32_e32 v137, v137
	v_exp_f32_e32 v128, v128
	v_mul_f32_e32 v122, v122, v129
	v_add_f32_e32 v129, 1.0, v136
	v_add_f32_e32 v136, 1.0, v137
	v_add_f32_e32 v128, 1.0, v128
	v_rcp_f32_e32 v136, v136
	v_rcp_f32_e32 v128, v128
	v_rcp_f32_e32 v129, v129
	v_mul_f32_e32 v122, v122, v123
	v_mul_f32_e32 v124, v124, v136
	v_mul_f32_e32 v128, v170, v128
	v_mul_f32_e32 v123, v126, v129
	v_mul_f32_e32 v124, v124, v125
	v_lshl_add_u32 v188, s38, 8, v1
	v_mul_f32_e32 v128, v128, v171
	v_mul_f32_e32 v123, v123, v127
	v_cvt_pk_bf16_f32 v126, v128, v122
	v_cvt_pk_bf16_f32 v127, v123, v124
	v_mov_b64_e32 v[124:125], s[12:13]
	v_mad_i64_i32 v[122:123], s[38:39], v188, s72, v[124:125]
	v_lshlrev_b64 v[138:139], 1, v[212:213]
	v_lshl_add_u64 v[122:123], v[122:123], 0, v[138:139]
	v_mov_b32_dpp v142, v118 row_ror:1 row_mask:0xf bank_mask:0xf
	v_mov_b32_dpp v225, v114 row_ror:1 row_mask:0xf bank_mask:0xf
	v_mov_b32_e32 v136, v118
	v_mov_b32_e32 v137, v114
	global_store_dwordx2 v[122:123], v[126:127], off
	v_mov_b32_dpp v143, v118 row_ror:2 row_mask:0xf bank_mask:0xf
	v_mov_b32_dpp v228, v114 row_ror:2 row_mask:0xf bank_mask:0xf
	v_cndmask_b32_e64 v127, v225, v238, s[8:9]
	v_cndmask_b32_e64 v126, v142, v135, s[8:9]
	v_pk_fma_f32 v[136:137], v[136:137], v[144:145], v[146:147]
	v_mov_b32_dpp v170, v119 row_ror:1 row_mask:0xf bank_mask:0xf
	v_cndmask_b32_e64 v129, v228, v239, s[6:7]
	v_cndmask_b32_e64 v128, v143, v172, s[6:7]
	v_pk_fma_f32 v[126:127], v[160:161], v[126:127], v[136:137]
	v_mov_b32_dpp v135, v115 row_ror:1 row_mask:0xf bank_mask:0xf
	v_mov_b32_e32 v114, v119
	v_mov_b32_dpp v171, v119 row_ror:2 row_mask:0xf bank_mask:0xf
	v_pk_fma_f32 v[126:127], v[162:163], v[128:129], v[126:127]
	v_mov_b32_dpp v172, v115 row_ror:2 row_mask:0xf bank_mask:0xf
	v_cndmask_b32_e64 v129, v135, v176, s[8:9]
	v_cndmask_b32_e64 v128, v170, v173, s[8:9]
	v_pk_fma_f32 v[114:115], v[114:115], v[158:159], v[130:131]
	v_cndmask_b32_e64 v137, v172, v226, s[6:7]
	v_cndmask_b32_e64 v136, v171, v174, s[6:7]
	v_pk_fma_f32 v[114:115], v[156:157], v[128:129], v[114:115]
	v_pk_fma_f32 v[114:115], v[154:155], v[136:137], v[114:115]
	v_mov_b32_dpp v173, v116 row_ror:1 row_mask:0xf bank_mask:0xf
	v_mov_b32_dpp v174, v116 row_ror:2 row_mask:0xf bank_mask:0xf
	v_mov_b32_e32 v137, v116
	v_mul_f32_e32 v116, 0xbfb8aa3b, v126
	v_mov_b32_dpp v179, v120 row_ror:1 row_mask:0xf bank_mask:0xf
	v_mov_b32_dpp v212, v120 row_ror:2 row_mask:0xf bank_mask:0xf
	v_mov_b32_e32 v136, v120
	v_exp_f32_e32 v120, v116
	v_cndmask_b32_e64 v119, v173, v177, s[8:9]
	v_add_f32_e32 v120, 1.0, v120
	v_mov_b32_dpp v213, v121 row_ror:1 row_mask:0xf bank_mask:0xf
	v_mov_b32_dpp v224, v121 row_ror:2 row_mask:0xf bank_mask:0xf
	v_cndmask_b32_e64 v118, v179, v175, s[8:9]
	v_pk_fma_f32 v[136:137], v[136:137], v[140:141], v[164:165]
	v_mov_b32_e32 v116, v121
	v_rcp_f32_e32 v120, v120
	v_mul_f32_e32 v121, 0xbfb8aa3b, v114
	v_cndmask_b32_e64 v129, v174, v227, s[6:7]
	v_cndmask_b32_e64 v128, v212, v232, s[6:7]
	v_pk_fma_f32 v[118:119], v[166:167], v[118:119], v[136:137]
	v_mov_b32_dpp v175, v117 row_ror:1 row_mask:0xf bank_mask:0xf
	v_exp_f32_e32 v121, v121
	v_pk_fma_f32 v[118:119], v[168:169], v[128:129], v[118:119]
	v_mov_b32_dpp v176, v117 row_ror:2 row_mask:0xf bank_mask:0xf
	v_cndmask_b32_e64 v129, v175, v178, s[8:9]
	v_cndmask_b32_e64 v128, v213, v234, s[8:9]
	v_pk_fma_f32 v[116:117], v[116:117], v[152:153], v[132:133]
	v_cndmask_b32_e64 v137, v176, v223, s[6:7]
	v_cndmask_b32_e64 v136, v224, v236, s[6:7]
	v_pk_fma_f32 v[116:117], v[150:151], v[128:129], v[116:117]
	v_mul_f32_e32 v120, v126, v120
	v_pk_fma_f32 v[116:117], v[148:149], v[136:137], v[116:117]
	v_mul_f32_e32 v120, v120, v127
	v_add_f32_e32 v121, 1.0, v121
	v_mul_f32_e32 v126, 0xbfb8aa3b, v118
	v_mul_f32_e32 v127, 0xbfb8aa3b, v116
	v_rcp_f32_e32 v121, v121
	v_exp_f32_e32 v126, v126
	v_exp_f32_e32 v127, v127
	v_mul_f32_e32 v114, v114, v121
	v_add_f32_e32 v121, 1.0, v126
	v_add_f32_e32 v126, 1.0, v127
	v_rcp_f32_e32 v121, v121
	v_rcp_f32_e32 v126, v126
	v_mul_f32_e32 v114, v114, v115
	v_cvt_pk_bf16_f32 v114, v120, v114
	v_mul_f32_e32 v115, v118, v121
	v_mul_f32_e32 v116, v116, v126
	v_mul_f32_e32 v115, v115, v119
	v_mul_f32_e32 v116, v116, v117
	v_or_b32_e32 v117, 16, v188
	v_cvt_pk_bf16_f32 v115, v115, v116
	v_mad_i64_i32 v[116:117], s[38:39], v117, s72, v[124:125]
	v_lshl_add_u64 v[118:119], v[116:117], 0, v[138:139]
	v_mov_b32_dpp v126, v110 row_ror:1 row_mask:0xf bank_mask:0xf
	v_mov_b32_dpp v223, v106 row_ror:1 row_mask:0xf bank_mask:0xf
	v_mov_b32_e32 v120, v110
	v_mov_b32_e32 v121, v106
	global_store_dwordx2 v[118:119], v[114:115], off
	v_mov_b32_dpp v127, v110 row_ror:2 row_mask:0xf bank_mask:0xf
	v_mov_b32_dpp v226, v106 row_ror:2 row_mask:0xf bank_mask:0xf
	v_cndmask_b32_e64 v115, v223, v225, s[8:9]
	v_cndmask_b32_e64 v114, v126, v142, s[8:9]
	v_pk_fma_f32 v[120:121], v[120:121], v[144:145], v[146:147]
	v_mov_b32_dpp v128, v111 row_ror:1 row_mask:0xf bank_mask:0xf
	v_cndmask_b32_e64 v117, v226, v228, s[6:7]
	v_cndmask_b32_e64 v116, v127, v143, s[6:7]
	v_pk_fma_f32 v[114:115], v[160:161], v[114:115], v[120:121]
	v_mov_b32_dpp v142, v107 row_ror:1 row_mask:0xf bank_mask:0xf
	v_mov_b32_e32 v106, v111
	v_mov_b32_dpp v129, v111 row_ror:2 row_mask:0xf bank_mask:0xf
	v_pk_fma_f32 v[114:115], v[162:163], v[116:117], v[114:115]
	v_mov_b32_dpp v143, v107 row_ror:2 row_mask:0xf bank_mask:0xf
	v_cndmask_b32_e64 v117, v142, v135, s[8:9]
	v_cndmask_b32_e64 v116, v128, v170, s[8:9]
	v_pk_fma_f32 v[106:107], v[106:107], v[158:159], v[130:131]
	v_cndmask_b32_e64 v121, v143, v172, s[6:7]
	v_cndmask_b32_e64 v120, v129, v171, s[6:7]
	v_pk_fma_f32 v[106:107], v[156:157], v[116:117], v[106:107]
	v_pk_fma_f32 v[106:107], v[154:155], v[120:121], v[106:107]
	v_mov_b32_dpp v135, v108 row_ror:1 row_mask:0xf bank_mask:0xf
	v_mov_b32_dpp v170, v108 row_ror:2 row_mask:0xf bank_mask:0xf
	v_mov_b32_e32 v121, v108
	v_mul_f32_e32 v108, 0xbfb8aa3b, v114
	v_exp_f32_e32 v172, v108
	v_mov_b32_dpp v136, v112 row_ror:1 row_mask:0xf bank_mask:0xf
	v_mov_b32_e32 v120, v112
	v_mov_b32_dpp v137, v112 row_ror:2 row_mask:0xf bank_mask:0xf
	v_cndmask_b32_e64 v111, v135, v173, s[8:9]
	v_cndmask_b32_e64 v110, v136, v179, s[8:9]
	v_pk_fma_f32 v[120:121], v[120:121], v[140:141], v[164:165]
	v_mov_b32_dpp v177, v113 row_ror:1 row_mask:0xf bank_mask:0xf
	v_cndmask_b32_e64 v117, v170, v174, s[6:7]
	v_cndmask_b32_e64 v116, v137, v212, s[6:7]
	v_pk_fma_f32 v[110:111], v[166:167], v[110:111], v[120:121]
	v_mov_b32_dpp v112, v109 row_ror:1 row_mask:0xf bank_mask:0xf
	v_mov_b32_e32 v108, v113
	v_mov_b32_dpp v178, v113 row_ror:2 row_mask:0xf bank_mask:0xf
	v_pk_fma_f32 v[110:111], v[168:169], v[116:117], v[110:111]
	v_mov_b32_dpp v171, v109 row_ror:2 row_mask:0xf bank_mask:0xf
	v_cndmask_b32_e64 v117, v112, v175, s[8:9]
	v_cndmask_b32_e64 v116, v177, v213, s[8:9]
	v_pk_fma_f32 v[108:109], v[108:109], v[152:153], v[132:133]
	v_add_f32_e32 v113, 1.0, v172
	v_pk_fma_f32 v[108:109], v[150:151], v[116:117], v[108:109]
	v_rcp_f32_e32 v113, v113
	v_mul_f32_e32 v116, 0xbfb8aa3b, v106
	v_exp_f32_e32 v116, v116
	v_cndmask_b32_e64 v121, v171, v176, s[6:7]
	v_cndmask_b32_e64 v120, v178, v224, s[6:7]
	v_pk_fma_f32 v[108:109], v[148:149], v[120:121], v[108:109]
	v_mul_f32_e32 v113, v114, v113
	v_mul_f32_e32 v113, v113, v115
	v_add_f32_e32 v114, 1.0, v116
	v_mul_f32_e32 v115, 0xbfb8aa3b, v110
	v_mul_f32_e32 v116, 0xbfb8aa3b, v108
	v_rcp_f32_e32 v114, v114
	v_exp_f32_e32 v115, v115
	v_exp_f32_e32 v116, v116
	v_mul_f32_e32 v106, v106, v114
	v_add_f32_e32 v114, 1.0, v115
	v_add_f32_e32 v115, 1.0, v116
	v_rcp_f32_e32 v114, v114
	v_rcp_f32_e32 v115, v115
	v_mul_f32_e32 v106, v106, v107
	v_cvt_pk_bf16_f32 v106, v113, v106
	v_mul_f32_e32 v107, v110, v114
	v_mul_f32_e32 v108, v108, v115
	v_mul_f32_e32 v107, v107, v111
	v_mul_f32_e32 v108, v108, v109
	v_or_b32_e32 v109, 32, v188
	v_cvt_pk_bf16_f32 v107, v107, v108
	v_mad_i64_i32 v[108:109], s[38:39], v109, s72, v[124:125]
	v_lshl_add_u64 v[120:121], v[108:109], 0, v[138:139]
	global_store_dwordx2 v[120:121], v[106:107], off
	v_mov_b32_dpp v106, v102 row_ror:1 row_mask:0xf bank_mask:0xf
	v_mov_b32_dpp v107, v98 row_ror:1 row_mask:0xf bank_mask:0xf
	v_mov_b32_e32 v110, v102
	v_mov_b32_e32 v111, v98
	v_mov_b32_dpp v108, v102 row_ror:2 row_mask:0xf bank_mask:0xf
	v_mov_b32_dpp v109, v98 row_ror:2 row_mask:0xf bank_mask:0xf
	v_cndmask_b32_e64 v107, v107, v223, s[8:9]
	v_cndmask_b32_e64 v106, v106, v126, s[8:9]
	v_pk_fma_f32 v[110:111], v[110:111], v[144:145], v[146:147]
	v_cndmask_b32_e64 v109, v109, v226, s[6:7]
	v_cndmask_b32_e64 v108, v108, v127, s[6:7]
	v_pk_fma_f32 v[106:107], v[160:161], v[106:107], v[110:111]
	v_mov_b32_dpp v98, v99 row_ror:1 row_mask:0xf bank_mask:0xf
	v_mov_b32_dpp v113, v103 row_ror:1 row_mask:0xf bank_mask:0xf
	v_pk_fma_f32 v[106:107], v[162:163], v[108:109], v[106:107]
	v_cndmask_b32_e64 v109, v98, v142, s[8:9]
	v_mov_b32_e32 v98, v103
	v_mov_b32_dpp v114, v103 row_ror:2 row_mask:0xf bank_mask:0xf
	v_mov_b32_dpp v102, v99 row_ror:2 row_mask:0xf bank_mask:0xf
	v_cndmask_b32_e64 v108, v113, v128, s[8:9]
	v_pk_fma_f32 v[98:99], v[98:99], v[158:159], v[130:131]
	v_cndmask_b32_e64 v111, v102, v143, s[6:7]
	v_cndmask_b32_e64 v110, v114, v129, s[6:7]
	v_pk_fma_f32 v[98:99], v[156:157], v[108:109], v[98:99]
	v_mov_b32_dpp v115, v104 row_ror:1 row_mask:0xf bank_mask:0xf
	v_pk_fma_f32 v[98:99], v[154:155], v[110:111], v[98:99]
	v_mov_b32_dpp v102, v100 row_ror:1 row_mask:0xf bank_mask:0xf
	v_mov_b32_e32 v110, v104
	v_mov_b32_e32 v111, v100
	v_mov_b32_dpp v116, v104 row_ror:2 row_mask:0xf bank_mask:0xf
	v_mov_b32_dpp v108, v100 row_ror:2 row_mask:0xf bank_mask:0xf
	v_cndmask_b32_e64 v103, v102, v135, s[8:9]
	v_cndmask_b32_e64 v102, v115, v136, s[8:9]
	v_pk_fma_f32 v[110:111], v[110:111], v[140:141], v[164:165]
	v_cndmask_b32_e64 v109, v108, v170, s[6:7]
	v_cndmask_b32_e64 v108, v116, v137, s[6:7]
	v_pk_fma_f32 v[102:103], v[166:167], v[102:103], v[110:111]
	v_mov_b32_dpp v100, v101 row_ror:1 row_mask:0xf bank_mask:0xf
	v_pk_fma_f32 v[102:103], v[168:169], v[108:109], v[102:103]
	v_cndmask_b32_e64 v109, v100, v112, s[8:9]
	v_mov_b32_dpp v104, v101 row_ror:2 row_mask:0xf bank_mask:0xf
	v_mul_f32_e32 v100, 0xbfb8aa3b, v106
	v_cndmask_b32_e64 v111, v104, v171, s[6:7]
	v_exp_f32_e32 v104, v100
	v_mov_b32_dpp v117, v105 row_ror:1 row_mask:0xf bank_mask:0xf
	v_mov_b32_e32 v100, v105
	v_add_f32_e32 v104, 1.0, v104
	v_mov_b32_dpp v172, v105 row_ror:2 row_mask:0xf bank_mask:0xf
	v_rcp_f32_e32 v104, v104
	v_mul_f32_e32 v105, 0xbfb8aa3b, v98
	v_exp_f32_e32 v105, v105
	v_cndmask_b32_e64 v108, v117, v177, s[8:9]
	v_pk_fma_f32 v[100:101], v[100:101], v[152:153], v[132:133]
	v_cndmask_b32_e64 v110, v172, v178, s[6:7]
	v_pk_fma_f32 v[100:101], v[150:151], v[108:109], v[100:101]
	v_mul_f32_e32 v104, v106, v104
	v_pk_fma_f32 v[100:101], v[148:149], v[110:111], v[100:101]
	v_mul_f32_e32 v104, v104, v107
	v_add_f32_e32 v105, 1.0, v105
	v_mul_f32_e32 v106, 0xbfb8aa3b, v102
	v_mul_f32_e32 v107, 0xbfb8aa3b, v100
	v_rcp_f32_e32 v105, v105
	v_exp_f32_e32 v106, v106
	v_exp_f32_e32 v107, v107
	v_mov_b32_e32 v134, 0
	v_mul_f32_e32 v98, v98, v105
	v_add_f32_e32 v105, 1.0, v106
	v_add_f32_e32 v106, 1.0, v107
	v_rcp_f32_e32 v105, v105
	v_rcp_f32_e32 v106, v106
	v_mul_f32_e32 v98, v98, v99
	v_cvt_pk_bf16_f32 v98, v104, v98
	v_mul_f32_e32 v99, v102, v105
	v_mul_f32_e32 v100, v100, v106
	v_mul_f32_e32 v99, v99, v103
	v_mul_f32_e32 v100, v100, v101
	v_or_b32_e32 v101, 48, v188
	v_cvt_pk_bf16_f32 v99, v99, v100
	v_mad_i64_i32 v[100:101], s[38:39], v101, s72, v[124:125]
	v_lshl_add_u64 v[124:125], v[100:101], 0, v[138:139]
	global_store_dwordx2 v[124:125], v[98:99], off
	v_mov_b32_e32 v100, 0
	v_mov_b32_e32 v101, 0
	v_mov_b32_e32 v102, 0
	v_mov_b32_e32 v103, 0
	s_and_saveexec_b64 s[38:39], s[4:5]
	ds_read_b128 v[100:103], v216
	s_or_b64 exec, exec, s[38:39]
	v_mov_b32_e32 v135, 0
	v_mov_b32_e32 v136, 0
	v_mov_b32_e32 v137, 0
	s_and_saveexec_b64 s[38:39], s[4:5]
	ds_read_b128 v[134:137], v216 offset:512
	s_or_b64 exec, exec, s[38:39]
	s_waitcnt lgkmcnt(0)
	v_mov_b32_dpp v116, v102 row_ror:1 row_mask:0xf bank_mask:0xf
	v_mov_b32_dpp v126, v102 row_ror:2 row_mask:0xf bank_mask:0xf
	v_mov_b32_dpp v108, v94 row_ror:1 row_mask:0xf bank_mask:0xf
	v_mov_b32_dpp v106, v100 row_ror:1 row_mask:0xf bank_mask:0xf
	v_mov_b32_e32 v104, v94
	v_mov_b32_e32 v105, v90
	v_mov_b32_dpp v143, v90 row_ror:1 row_mask:0xf bank_mask:0xf
	v_mov_b32_dpp v102, v134 row_ror:1 row_mask:0xf bank_mask:0xf
	v_mov_b32_dpp v170, v90 row_ror:2 row_mask:0xf bank_mask:0xf
	v_mov_b32_dpp v109, v94 row_ror:2 row_mask:0xf bank_mask:0xf
	v_mov_b32_dpp v110, v100 row_ror:2 row_mask:0xf bank_mask:0xf
	v_mov_b32_dpp v128, v103 row_ror:1 row_mask:0xf bank_mask:0xf
	v_mov_b32_dpp v142, v103 row_ror:2 row_mask:0xf bank_mask:0xf
	v_mov_b32_dpp v90, v134 row_ror:2 row_mask:0xf bank_mask:0xf
	v_cndmask_b32_e64 v103, v143, v102, s[8:9]
	v_cndmask_b32_e64 v102, v108, v106, s[8:9]
	v_pk_fma_f32 v[104:105], v[104:105], v[144:145], v[146:147]
	v_cndmask_b32_e64 v107, v170, v90, s[6:7]
	v_cndmask_b32_e64 v106, v109, v110, s[6:7]
	v_pk_fma_f32 v[102:103], v[160:161], v[102:103], v[104:105]
	v_pk_fma_f32 v[102:103], v[162:163], v[106:107], v[102:103]
	v_mov_b32_dpp v111, v95 row_ror:1 row_mask:0xf bank_mask:0xf
	v_mov_b32_dpp v112, v101 row_ror:1 row_mask:0xf bank_mask:0xf
	v_mov_b32_dpp v113, v95 row_ror:2 row_mask:0xf bank_mask:0xf
	v_mov_b32_e32 v94, v95
	v_mov_b32_e32 v95, v91
	v_mov_b32_dpp v106, v91 row_ror:1 row_mask:0xf bank_mask:0xf
	v_mov_b32_dpp v90, v135 row_ror:1 row_mask:0xf bank_mask:0xf
	v_pk_fma_f32 v[94:95], v[94:95], v[158:159], v[130:131]
	v_mov_b32_dpp v107, v91 row_ror:2 row_mask:0xf bank_mask:0xf
	v_cndmask_b32_e64 v91, v106, v90, s[8:9]
	v_cndmask_b32_e64 v90, v111, v112, s[8:9]
	v_pk_fma_f32 v[90:91], v[156:157], v[90:91], v[94:95]
	v_mov_b32_dpp v114, v101 row_ror:2 row_mask:0xf bank_mask:0xf
	v_mov_b32_dpp v115, v96 row_ror:1 row_mask:0xf bank_mask:0xf
	v_mov_b32_e32 v100, v96
	v_mov_b32_e32 v101, v92
	v_mov_b32_dpp v104, v135 row_ror:2 row_mask:0xf bank_mask:0xf
	v_mov_b32_dpp v110, v92 row_ror:1 row_mask:0xf bank_mask:0xf
	v_mov_b32_dpp v94, v136 row_ror:1 row_mask:0xf bank_mask:0xf
	v_mov_b32_dpp v112, v92 row_ror:2 row_mask:0xf bank_mask:0xf
	v_mov_b32_dpp v117, v96 row_ror:2 row_mask:0xf bank_mask:0xf
	v_cndmask_b32_e64 v105, v107, v104, s[6:7]
	v_cndmask_b32_e64 v104, v113, v114, s[6:7]
	v_mov_b32_dpp v92, v136 row_ror:2 row_mask:0xf bank_mask:0xf
	v_cndmask_b32_e64 v95, v110, v94, s[8:9]
	v_cndmask_b32_e64 v94, v115, v116, s[8:9]
	v_pk_fma_f32 v[100:101], v[100:101], v[140:141], v[164:165]
	v_pk_fma_f32 v[90:91], v[154:155], v[104:105], v[90:91]
	v_cndmask_b32_e64 v105, v112, v92, s[6:7]
	v_cndmask_b32_e64 v104, v117, v126, s[6:7]
	v_pk_fma_f32 v[94:95], v[166:167], v[94:95], v[100:101]
	v_pk_fma_f32 v[94:95], v[168:169], v[104:105], v[94:95]
	v_mov_b32_dpp v127, v97 row_ror:1 row_mask:0xf bank_mask:0xf
	v_mov_b32_dpp v129, v97 row_ror:2 row_mask:0xf bank_mask:0xf
	v_mov_b32_e32 v96, v97
	v_mov_b32_e32 v97, v93
	v_mov_b32_dpp v104, v93 row_ror:1 row_mask:0xf bank_mask:0xf
	v_mov_b32_dpp v92, v137 row_ror:1 row_mask:0xf bank_mask:0xf
	v_pk_fma_f32 v[96:97], v[96:97], v[152:153], v[132:133]
	v_mov_b32_dpp v105, v93 row_ror:2 row_mask:0xf bank_mask:0xf
	v_cndmask_b32_e64 v93, v104, v92, s[8:9]
	v_cndmask_b32_e64 v92, v127, v128, s[8:9]
	v_pk_fma_f32 v[92:93], v[150:151], v[92:93], v[96:97]
	v_mul_f32_e32 v97, 0xbfb8aa3b, v90
	v_mov_b32_dpp v100, v137 row_ror:2 row_mask:0xf bank_mask:0xf
	v_exp_f32_e32 v97, v97
	v_cndmask_b32_e64 v101, v105, v100, s[6:7]
	v_mul_f32_e32 v100, 0xbfb8aa3b, v102
	v_exp_f32_e32 v114, v100
	v_cndmask_b32_e64 v100, v129, v142, s[6:7]
	v_pk_fma_f32 v[92:93], v[148:149], v[100:101], v[92:93]
	v_add_f32_e32 v97, 1.0, v97
	v_mul_f32_e32 v100, 0xbfb8aa3b, v94
	v_mul_f32_e32 v101, 0xbfb8aa3b, v92
	v_rcp_f32_e32 v97, v97
	v_exp_f32_e32 v100, v100
	v_exp_f32_e32 v101, v101
	v_add_f32_e32 v96, 1.0, v114
	v_mul_f32_e32 v90, v90, v97
	v_add_f32_e32 v97, 1.0, v100
	v_add_f32_e32 v100, 1.0, v101
	v_rcp_f32_e32 v97, v97
	v_rcp_f32_e32 v100, v100
	v_rcp_f32_e32 v96, v96
	v_mul_f32_e32 v90, v90, v91
	v_mul_f32_e32 v91, v94, v97
	v_mul_f32_e32 v92, v92, v100
	v_mul_f32_e32 v96, v102, v96
	v_mul_f32_e32 v91, v91, v95
	v_mul_f32_e32 v93, v92, v93
	v_add_u32_e32 v99, 0x80, v188
	v_mul_f32_e32 v96, v96, v103
	v_cvt_pk_bf16_f32 v92, v96, v90
	v_cvt_pk_bf16_f32 v93, v91, v93
	v_mov_b64_e32 v[90:91], s[12:13]
	v_mad_i64_i32 v[94:95], s[38:39], v99, s72, v[90:91]
	v_lshl_add_u64 v[96:97], v[94:95], 0, v[138:139]
	global_store_dwordx2 v[96:97], v[92:93], off
	v_mov_b32_dpp v99, v86 row_ror:1 row_mask:0xf bank_mask:0xf
	v_mov_b32_e32 v92, v86
	v_mov_b32_e32 v93, v82
	v_mov_b32_dpp v142, v82 row_ror:1 row_mask:0xf bank_mask:0xf
	v_mov_b32_dpp v114, v86 row_ror:2 row_mask:0xf bank_mask:0xf
	v_cndmask_b32_e64 v101, v142, v143, s[8:9]
	v_mov_b32_dpp v171, v82 row_ror:2 row_mask:0xf bank_mask:0xf
	v_cndmask_b32_e64 v100, v99, v108, s[8:9]
	v_pk_fma_f32 v[92:93], v[92:93], v[144:145], v[146:147]
	v_cndmask_b32_e64 v103, v171, v170, s[6:7]
	v_cndmask_b32_e64 v102, v114, v109, s[6:7]
	v_pk_fma_f32 v[92:93], v[160:161], v[100:101], v[92:93]
	v_pk_fma_f32 v[92:93], v[162:163], v[102:103], v[92:93]
	v_mov_b32_dpp v102, v83 row_ror:1 row_mask:0xf bank_mask:0xf
	v_mov_b32_dpp v116, v87 row_ror:1 row_mask:0xf bank_mask:0xf
	v_mov_b32_dpp v128, v87 row_ror:2 row_mask:0xf bank_mask:0xf
	v_mov_b32_e32 v86, v87
	v_mov_b32_e32 v87, v83
	v_mov_b32_dpp v103, v83 row_ror:2 row_mask:0xf bank_mask:0xf
	v_cndmask_b32_e64 v83, v102, v106, s[8:9]
	v_mov_b32_dpp v134, v88 row_ror:1 row_mask:0xf bank_mask:0xf
	v_mov_b32_e32 v94, v88
	v_mov_b32_e32 v95, v84
	v_cndmask_b32_e64 v82, v116, v111, s[8:9]
	v_cndmask_b32_e64 v101, v103, v107, s[6:7]
	v_pk_fma_f32 v[86:87], v[86:87], v[158:159], v[130:131]
	v_mov_b32_dpp v106, v84 row_ror:1 row_mask:0xf bank_mask:0xf
	v_mov_b32_dpp v135, v88 row_ror:2 row_mask:0xf bank_mask:0xf
	v_cndmask_b32_e64 v100, v128, v113, s[6:7]
	v_pk_fma_f32 v[82:83], v[156:157], v[82:83], v[86:87]
	v_mov_b32_dpp v107, v84 row_ror:2 row_mask:0xf bank_mask:0xf
	v_cndmask_b32_e64 v87, v106, v110, s[8:9]
	v_cndmask_b32_e64 v86, v134, v115, s[8:9]
	v_pk_fma_f32 v[94:95], v[94:95], v[140:141], v[164:165]
	v_pk_fma_f32 v[82:83], v[154:155], v[100:101], v[82:83]
	v_cndmask_b32_e64 v101, v107, v112, s[6:7]
	v_cndmask_b32_e64 v100, v135, v117, s[6:7]
	v_pk_fma_f32 v[86:87], v[166:167], v[86:87], v[94:95]
	v_pk_fma_f32 v[86:87], v[168:169], v[100:101], v[86:87]
	v_mov_b32_dpp v100, v85 row_ror:1 row_mask:0xf bank_mask:0xf
	v_mul_f32_e32 v94, 0xbfb8aa3b, v92
	v_mov_b32_dpp v136, v89 row_ror:1 row_mask:0xf bank_mask:0xf
	v_mov_b32_dpp v137, v89 row_ror:2 row_mask:0xf bank_mask:0xf
	v_mov_b32_e32 v88, v89
	v_mov_b32_e32 v89, v85
	v_mov_b32_dpp v101, v85 row_ror:2 row_mask:0xf bank_mask:0xf
	v_cndmask_b32_e64 v85, v100, v104, s[8:9]
	v_exp_f32_e32 v104, v94
	v_cndmask_b32_e64 v84, v136, v127, s[8:9]
	v_pk_fma_f32 v[88:89], v[88:89], v[152:153], v[132:133]
	v_cndmask_b32_e64 v95, v101, v105, s[6:7]
	v_pk_fma_f32 v[84:85], v[150:151], v[84:85], v[88:89]
	v_add_f32_e32 v88, 1.0, v104
	v_rcp_f32_e32 v88, v88
	v_mul_f32_e32 v89, 0xbfb8aa3b, v82
	v_exp_f32_e32 v89, v89
	v_cndmask_b32_e64 v94, v137, v129, s[6:7]
	v_pk_fma_f32 v[84:85], v[148:149], v[94:95], v[84:85]
	v_mul_f32_e32 v88, v92, v88
	v_mul_f32_e32 v88, v88, v93
	v_add_f32_e32 v89, 1.0, v89
	v_mul_f32_e32 v92, 0xbfb8aa3b, v86
	v_mul_f32_e32 v93, 0xbfb8aa3b, v84
	v_rcp_f32_e32 v89, v89
	v_exp_f32_e32 v92, v92
	v_exp_f32_e32 v93, v93
	v_mul_f32_e32 v82, v82, v89
	v_add_f32_e32 v89, 1.0, v92
	v_add_f32_e32 v92, 1.0, v93
	v_rcp_f32_e32 v89, v89
	v_rcp_f32_e32 v92, v92
	v_mul_f32_e32 v82, v82, v83
	v_cvt_pk_bf16_f32 v82, v88, v82
	v_mul_f32_e32 v83, v86, v89
	v_mul_f32_e32 v84, v84, v92
	v_mul_f32_e32 v83, v83, v87
	v_mul_f32_e32 v84, v84, v85
	v_add_u32_e32 v85, 0x90, v188
	v_cvt_pk_bf16_f32 v83, v83, v84
	v_mad_i64_i32 v[84:85], s[38:39], v85, s72, v[90:91]
	v_lshl_add_u64 v[126:127], v[84:85], 0, v[138:139]
	global_store_dwordx2 v[126:127], v[82:83], off
	v_mov_b32_dpp v92, v78 row_ror:1 row_mask:0xf bank_mask:0xf
	v_mov_b32_e32 v82, v78
	v_mov_b32_e32 v83, v74
	v_mov_b32_dpp v110, v74 row_ror:1 row_mask:0xf bank_mask:0xf
	v_mov_b32_dpp v93, v78 row_ror:2 row_mask:0xf bank_mask:0xf
	v_cndmask_b32_e64 v87, v110, v142, s[8:9]
	v_mov_b32_dpp v111, v74 row_ror:2 row_mask:0xf bank_mask:0xf
	v_cndmask_b32_e64 v86, v92, v99, s[8:9]
	v_pk_fma_f32 v[82:83], v[82:83], v[144:145], v[146:147]
	v_cndmask_b32_e64 v89, v111, v171, s[6:7]
	v_cndmask_b32_e64 v88, v93, v114, s[6:7]
	v_pk_fma_f32 v[82:83], v[160:161], v[86:87], v[82:83]
	v_pk_fma_f32 v[82:83], v[162:163], v[88:89], v[82:83]
	v_mov_b32_dpp v94, v79 row_ror:1 row_mask:0xf bank_mask:0xf
	v_mov_b32_dpp v95, v79 row_ror:2 row_mask:0xf bank_mask:0xf
	v_mov_b32_e32 v78, v79
	v_mov_b32_e32 v79, v75
	v_mov_b32_dpp v88, v75 row_ror:1 row_mask:0xf bank_mask:0xf
	v_mov_b32_dpp v104, v80 row_ror:1 row_mask:0xf bank_mask:0xf
	v_mov_b32_e32 v84, v80
	v_mov_b32_e32 v85, v76
	v_mov_b32_dpp v89, v75 row_ror:2 row_mask:0xf bank_mask:0xf
	v_cndmask_b32_e64 v75, v88, v102, s[8:9]
	v_cndmask_b32_e64 v74, v94, v116, s[8:9]
	v_pk_fma_f32 v[78:79], v[78:79], v[158:159], v[130:131]
	v_mov_b32_dpp v99, v76 row_ror:1 row_mask:0xf bank_mask:0xf
	v_mov_b32_dpp v105, v80 row_ror:2 row_mask:0xf bank_mask:0xf
	v_cndmask_b32_e64 v87, v89, v103, s[6:7]
	v_cndmask_b32_e64 v86, v95, v128, s[6:7]
	v_pk_fma_f32 v[74:75], v[156:157], v[74:75], v[78:79]
	v_mov_b32_dpp v102, v76 row_ror:2 row_mask:0xf bank_mask:0xf
	v_cndmask_b32_e64 v79, v99, v106, s[8:9]
	v_cndmask_b32_e64 v78, v104, v134, s[8:9]
	v_pk_fma_f32 v[84:85], v[84:85], v[140:141], v[164:165]
	v_pk_fma_f32 v[74:75], v[154:155], v[86:87], v[74:75]
	v_cndmask_b32_e64 v87, v102, v107, s[6:7]
	v_cndmask_b32_e64 v86, v105, v135, s[6:7]
	v_pk_fma_f32 v[78:79], v[166:167], v[78:79], v[84:85]
	v_pk_fma_f32 v[78:79], v[168:169], v[86:87], v[78:79]
	v_mov_b32_dpp v86, v77 row_ror:1 row_mask:0xf bank_mask:0xf
	v_mul_f32_e32 v84, 0xbfb8aa3b, v82
	v_mov_b32_dpp v108, v81 row_ror:1 row_mask:0xf bank_mask:0xf
	v_mov_b32_dpp v109, v81 row_ror:2 row_mask:0xf bank_mask:0xf
	v_mov_b32_e32 v80, v81
	v_mov_b32_e32 v81, v77
	v_mov_b32_dpp v87, v77 row_ror:2 row_mask:0xf bank_mask:0xf
	v_cndmask_b32_e64 v77, v86, v100, s[8:9]
	v_exp_f32_e32 v100, v84
	v_cndmask_b32_e64 v76, v108, v136, s[8:9]
	v_pk_fma_f32 v[80:81], v[80:81], v[152:153], v[132:133]
	v_cndmask_b32_e64 v85, v87, v101, s[6:7]
	v_pk_fma_f32 v[76:77], v[150:151], v[76:77], v[80:81]
	v_add_f32_e32 v80, 1.0, v100
	v_rcp_f32_e32 v80, v80
	v_mul_f32_e32 v81, 0xbfb8aa3b, v74
	v_exp_f32_e32 v81, v81
	v_cndmask_b32_e64 v84, v109, v137, s[6:7]
	v_pk_fma_f32 v[76:77], v[148:149], v[84:85], v[76:77]
	v_mul_f32_e32 v80, v82, v80
	v_mul_f32_e32 v80, v80, v83
	v_add_f32_e32 v81, 1.0, v81
	v_mul_f32_e32 v82, 0xbfb8aa3b, v78
	v_mul_f32_e32 v83, 0xbfb8aa3b, v76
	v_rcp_f32_e32 v81, v81
	v_exp_f32_e32 v82, v82
	v_exp_f32_e32 v83, v83
	v_mul_f32_e32 v74, v74, v81
	v_add_f32_e32 v81, 1.0, v82
	v_add_f32_e32 v82, 1.0, v83
	v_rcp_f32_e32 v81, v81
	v_rcp_f32_e32 v82, v82
	v_mul_f32_e32 v74, v74, v75
	v_cvt_pk_bf16_f32 v74, v80, v74
	v_mul_f32_e32 v75, v78, v81
	v_mul_f32_e32 v76, v76, v82
	v_mul_f32_e32 v75, v75, v79
	v_mul_f32_e32 v76, v76, v77
	v_add_u32_e32 v77, 0xa0, v188
	v_cvt_pk_bf16_f32 v75, v75, v76
	v_mad_i64_i32 v[76:77], s[38:39], v77, s72, v[90:91]
	v_lshl_add_u64 v[128:129], v[76:77], 0, v[138:139]
	global_store_dwordx2 v[128:129], v[74:75], off
	v_mov_b32_dpp v78, v70 row_ror:1 row_mask:0xf bank_mask:0xf
	v_mov_b32_e32 v74, v70
	v_mov_b32_e32 v75, v66
	v_mov_b32_dpp v79, v66 row_ror:1 row_mask:0xf bank_mask:0xf
	v_mov_b32_dpp v81, v66 row_ror:2 row_mask:0xf bank_mask:0xf
	v_cndmask_b32_e64 v79, v79, v110, s[8:9]
	v_cndmask_b32_e64 v78, v78, v92, s[8:9]
	v_pk_fma_f32 v[74:75], v[74:75], v[144:145], v[146:147]
	v_mov_b32_dpp v80, v70 row_ror:2 row_mask:0xf bank_mask:0xf
	v_mov_b32_dpp v82, v71 row_ror:1 row_mask:0xf bank_mask:0xf
	v_mov_b32_dpp v83, v71 row_ror:2 row_mask:0xf bank_mask:0xf
	v_mov_b32_e32 v70, v71
	v_mov_b32_e32 v71, v67
	v_pk_fma_f32 v[74:75], v[160:161], v[78:79], v[74:75]
	v_mov_b32_dpp v66, v67 row_ror:1 row_mask:0xf bank_mask:0xf
	v_pk_fma_f32 v[70:71], v[70:71], v[158:159], v[130:131]
	v_mov_b32_dpp v84, v72 row_ror:1 row_mask:0xf bank_mask:0xf
	v_mov_b32_dpp v78, v67 row_ror:2 row_mask:0xf bank_mask:0xf
	v_cndmask_b32_e64 v67, v66, v88, s[8:9]
	v_cndmask_b32_e64 v66, v82, v94, s[8:9]
	v_pk_fma_f32 v[66:67], v[156:157], v[66:67], v[70:71]
	v_mov_b32_e32 v76, v72
	v_mov_b32_e32 v77, v68
	v_mov_b32_dpp v70, v68 row_ror:1 row_mask:0xf bank_mask:0xf
	v_cndmask_b32_e64 v79, v78, v89, s[6:7]
	v_cndmask_b32_e64 v78, v83, v95, s[6:7]
	v_cndmask_b32_e64 v71, v70, v99, s[8:9]
	v_cndmask_b32_e64 v70, v84, v104, s[8:9]
	v_pk_fma_f32 v[76:77], v[76:77], v[140:141], v[164:165]
	v_cndmask_b32_e64 v81, v81, v111, s[6:7]
	v_cndmask_b32_e64 v80, v80, v93, s[6:7]
	v_pk_fma_f32 v[66:67], v[154:155], v[78:79], v[66:67]
	v_pk_fma_f32 v[70:71], v[166:167], v[70:71], v[76:77]
	v_mov_b32_dpp v85, v72 row_ror:2 row_mask:0xf bank_mask:0xf
	v_pk_fma_f32 v[74:75], v[162:163], v[80:81], v[74:75]
	v_mov_b32_dpp v78, v68 row_ror:2 row_mask:0xf bank_mask:0xf
	v_mov_b32_dpp v76, v69 row_ror:2 row_mask:0xf bank_mask:0xf
	v_cndmask_b32_e64 v79, v78, v102, s[6:7]
	v_cndmask_b32_e64 v78, v85, v105, s[6:7]
	v_cndmask_b32_e64 v77, v76, v87, s[6:7]
	v_mul_f32_e32 v76, 0xbfb8aa3b, v74
	v_pk_fma_f32 v[70:71], v[168:169], v[78:79], v[70:71]
	v_exp_f32_e32 v78, v76
	v_mov_b32_dpp v100, v73 row_ror:1 row_mask:0xf bank_mask:0xf
	v_mov_b32_dpp v101, v73 row_ror:2 row_mask:0xf bank_mask:0xf
	v_mov_b32_e32 v72, v73
	v_mov_b32_e32 v73, v69
	v_mov_b32_dpp v68, v69 row_ror:1 row_mask:0xf bank_mask:0xf
	v_cndmask_b32_e64 v69, v68, v86, s[8:9]
	v_cndmask_b32_e64 v68, v100, v108, s[8:9]
	v_pk_fma_f32 v[72:73], v[72:73], v[152:153], v[132:133]
	v_cndmask_b32_e64 v76, v101, v109, s[6:7]
	v_pk_fma_f32 v[68:69], v[150:151], v[68:69], v[72:73]
	v_add_f32_e32 v72, 1.0, v78
	v_rcp_f32_e32 v72, v72
	v_mul_f32_e32 v73, 0xbfb8aa3b, v66
	v_exp_f32_e32 v73, v73
	v_pk_fma_f32 v[68:69], v[148:149], v[76:77], v[68:69]
	v_mul_f32_e32 v72, v74, v72
	v_mul_f32_e32 v72, v72, v75
	v_add_f32_e32 v73, 1.0, v73
	v_mul_f32_e32 v74, 0xbfb8aa3b, v70
	v_mul_f32_e32 v75, 0xbfb8aa3b, v68
	v_rcp_f32_e32 v73, v73
	v_exp_f32_e32 v74, v74
	v_exp_f32_e32 v75, v75
	v_mov_b32_e32 v98, 0
	v_mul_f32_e32 v66, v66, v73
	v_add_f32_e32 v73, 1.0, v74
	v_add_f32_e32 v74, 1.0, v75
	v_rcp_f32_e32 v73, v73
	v_rcp_f32_e32 v74, v74
	v_mul_f32_e32 v66, v66, v67
	v_cvt_pk_bf16_f32 v66, v72, v66
	v_mul_f32_e32 v67, v70, v73
	v_mul_f32_e32 v68, v68, v74
	v_mul_f32_e32 v67, v67, v71
	v_mul_f32_e32 v68, v68, v69
	v_add_u32_e32 v69, 0xb0, v188
	v_cvt_pk_bf16_f32 v67, v67, v68
	v_mad_i64_i32 v[68:69], s[38:39], v69, s72, v[90:91]
	v_lshl_add_u64 v[130:131], v[68:69], 0, v[138:139]
	global_store_dwordx2 v[130:131], v[66:67], off
	v_add_co_u32_e32 v66, vcc, 0x15000, v206
	v_mov_b32_e32 v70, s94
	global_load_dwordx4 v[72:75], v[210:211], off offset:16
	global_load_dwordx4 v[80:83], v[206:207], off offset:16
	v_addc_co_u32_e32 v67, vcc, 0, v207, vcc
	v_add_co_u32_e32 v68, vcc, 0x2b000, v206
	s_nop 1
	v_addc_co_u32_e32 v69, vcc, 0, v207, vcc
	global_load_dwordx4 v[88:91], v[66:67], off offset:2064
	global_load_dwordx4 v[84:87], v[68:69], off offset:16
	v_add_co_u32_e32 v66, vcc, 0xa000, v210
	s_nop 1
	v_addc_co_u32_e32 v67, vcc, 0, v211, vcc
	v_add_co_u32_e32 v76, vcc, 0xa000, v206
	global_load_dwordx4 v[66:69], v[66:67], off offset:3088
	s_nop 0
	global_load_dwordx4 v[114:117], v[208:209], off offset:16
	global_load_dwordx4 v[92:95], v[208:209], off offset:528
	v_addc_co_u32_e32 v77, vcc, 0, v207, vcc
	v_add_co_u32_e32 v78, vcc, 0x20000, v206
	s_nop 1
	v_addc_co_u32_e32 v79, vcc, 0, v207, vcc
	global_load_dwordx4 v[106:109], v[76:77], off offset:3088
	global_load_dwordx4 v[102:105], v[78:79], off offset:1040
	v_add_co_u32_e32 v76, vcc, 0x35000, v206
	v_mov_b32_e32 v78, 0
	s_nop 0
	v_addc_co_u32_e32 v77, vcc, 0, v207, vcc
	global_load_dwordx4 v[110:113], v[76:77], off offset:3088
	v_mov_b32_e32 v76, 0
	v_mov_b32_e32 v77, 0
	v_mov_b32_e32 v79, 0
	s_and_saveexec_b64 s[38:39], s[26:27]
	ds_read_b128 v[76:79], v217
	s_or_b64 exec, exec, s[38:39]
	v_mov_b32_e32 v99, 0
	v_mov_b32_e32 v100, 0
	v_mov_b32_e32 v101, 0
	s_and_saveexec_b64 s[38:39], s[26:27]
	ds_read_b128 v[98:101], v217 offset:512
	s_or_b64 exec, exec, s[38:39]
	s_waitcnt vmcnt(4)
	v_pk_mul_f32 v[114:115], v[114:115], v[70:71] op_sel_hi:[1,0]
	v_pk_mul_f32 v[116:117], v[116:117], v[70:71] op_sel_hi:[1,0]
	v_pk_mul_f32 v[134:135], v[80:81], v[114:115]
	v_pk_mul_f32 v[138:139], v[114:115], v[88:89]
	v_pk_mul_f32 v[114:115], v[114:115], v[84:85]
	s_waitcnt vmcnt(3)
	v_pk_mul_f32 v[84:85], v[70:71], v[94:95] op_sel_hi:[0,1]
	v_pk_mul_f32 v[70:71], v[70:71], v[92:93] op_sel_hi:[0,1]
	v_pk_mul_f32 v[132:133], v[82:83], v[116:117]
	v_pk_mul_f32 v[136:137], v[116:117], v[90:91]
	v_pk_mul_f32 v[116:117], v[116:117], v[86:87]
	s_waitcnt vmcnt(2)
	v_pk_mul_f32 v[86:87], v[106:107], v[70:71]
	s_waitcnt vmcnt(1)
	v_pk_mul_f32 v[88:89], v[70:71], v[102:103]
	s_waitcnt vmcnt(0)
	v_pk_mul_f32 v[90:91], v[70:71], v[110:111]
	s_waitcnt lgkmcnt(0)
	v_mov_b32_dpp v92, v76 row_ror:1 row_mask:0xf bank_mask:0xf
	v_mov_b32_dpp v93, v76 row_ror:2 row_mask:0xf bank_mask:0xf
	v_mov_b32_dpp v106, v77 row_ror:1 row_mask:0xf bank_mask:0xf
	v_mov_b32_dpp v107, v77 row_ror:2 row_mask:0xf bank_mask:0xf
	v_pk_mul_f32 v[80:81], v[108:109], v[84:85]
	v_mov_b32_dpp v71, v62 row_ror:1 row_mask:0xf bank_mask:0xf
	v_mov_b32_dpp v110, v62 row_ror:2 row_mask:0xf bank_mask:0xf
	v_mov_b32_dpp v145, v58 row_ror:1 row_mask:0xf bank_mask:0xf
	v_mov_b32_dpp v76, v98 row_ror:1 row_mask:0xf bank_mask:0xf
	v_mov_b32_dpp v146, v58 row_ror:2 row_mask:0xf bank_mask:0xf
	v_mov_b32_dpp v77, v98 row_ror:2 row_mask:0xf bank_mask:0xf
	v_mov_b32_dpp v108, v78 row_ror:1 row_mask:0xf bank_mask:0xf
	v_mov_b32_dpp v109, v78 row_ror:2 row_mask:0xf bank_mask:0xf
	v_mov_b32_dpp v142, v79 row_ror:1 row_mask:0xf bank_mask:0xf
	v_mov_b32_dpp v144, v79 row_ror:2 row_mask:0xf bank_mask:0xf
	v_cndmask_b32_e64 v95, v145, v76, s[8:9]
	v_cndmask_b32_e64 v94, v71, v92, s[8:9]
	v_cndmask_b32_e64 v103, v146, v77, s[6:7]
	v_cndmask_b32_e64 v102, v110, v93, s[6:7]
	v_mov_b32_e32 v92, v62
	v_mov_b32_e32 v93, v58
	v_mov_b32_e32 v76, v114
	v_mov_b32_e32 v77, v90
	v_mov_b32_e32 v78, v72
	v_mov_b32_e32 v79, v66
	v_pk_mul_f32 v[82:83], v[84:85], v[104:105]
	v_pk_fma_f32 v[104:105], v[92:93], v[76:77], v[78:79]
	v_mov_b32_e32 v92, v138
	v_mov_b32_e32 v93, v88
	v_mov_b32_dpp v114, v59 row_ror:1 row_mask:0xf bank_mask:0xf
	v_mov_b32_dpp v58, v99 row_ror:1 row_mask:0xf bank_mask:0xf
	v_pk_mul_f32 v[84:85], v[84:85], v[112:113]
	v_mov_b32_dpp v111, v63 row_ror:1 row_mask:0xf bank_mask:0xf
	v_pk_fma_f32 v[104:105], v[92:93], v[94:95], v[104:105]
	v_mov_b32_e32 v94, v134
	v_mov_b32_dpp v62, v99 row_ror:2 row_mask:0xf bank_mask:0xf
	v_cndmask_b32_e64 v99, v114, v58, s[8:9]
	v_mov_b32_e32 v58, v63
	v_mov_b32_e32 v90, v115
	v_mov_b32_e32 v66, v73
	v_mov_b32_dpp v112, v63 row_ror:2 row_mask:0xf bank_mask:0xf
	v_mov_b32_e32 v95, v86
	v_mov_b32_dpp v134, v59 row_ror:2 row_mask:0xf bank_mask:0xf
	v_cndmask_b32_e64 v98, v111, v106, s[8:9]
	v_pk_fma_f32 v[58:59], v[58:59], v[90:91], v[66:67]
	v_mov_b32_e32 v88, v139
	v_pk_fma_f32 v[104:105], v[94:95], v[102:103], v[104:105]
	v_cndmask_b32_e64 v103, v134, v62, s[6:7]
	v_cndmask_b32_e64 v102, v112, v107, s[6:7]
	v_pk_fma_f32 v[58:59], v[88:89], v[98:99], v[58:59]
	v_mov_b32_e32 v86, v135
	v_pk_fma_f32 v[72:73], v[86:87], v[102:103], v[58:59]
	v_mov_b32_dpp v115, v60 row_ror:1 row_mask:0xf bank_mask:0xf
	v_mov_b32_dpp v135, v60 row_ror:2 row_mask:0xf bank_mask:0xf
	v_mov_b32_e32 v99, v60
	v_mov_b32_e32 v62, v74
	v_mov_b32_dpp v113, v64 row_ror:1 row_mask:0xf bank_mask:0xf
	v_mov_b32_dpp v140, v64 row_ror:2 row_mask:0xf bank_mask:0xf
	v_mov_b32_dpp v58, v100 row_ror:1 row_mask:0xf bank_mask:0xf
	v_mov_b32_dpp v59, v100 row_ror:2 row_mask:0xf bank_mask:0xf
	v_mov_b32_e32 v98, v64
	v_mov_b32_dpp v74, v61 row_ror:1 row_mask:0xf bank_mask:0xf
	v_mov_b32_dpp v60, v101 row_ror:1 row_mask:0xf bank_mask:0xf
	v_mov_b32_dpp v141, v65 row_ror:1 row_mask:0xf bank_mask:0xf
	v_mov_b32_dpp v143, v65 row_ror:2 row_mask:0xf bank_mask:0xf
	v_cndmask_b32_e64 v103, v115, v58, s[8:9]
	v_cndmask_b32_e64 v107, v135, v59, s[6:7]
	v_mov_b32_e32 v58, v116
	v_mov_b32_e32 v59, v84
	v_mov_b32_e32 v63, v68
	v_mov_b32_dpp v64, v101 row_ror:2 row_mask:0xf bank_mask:0xf
	v_cndmask_b32_e64 v101, v74, v60, s[8:9]
	v_mov_b32_e32 v60, v65
	v_mul_f32_e32 v65, 0xbfb8aa3b, v72
	v_cndmask_b32_e64 v102, v113, v108, s[8:9]
	v_cndmask_b32_e64 v106, v140, v109, s[6:7]
	v_pk_fma_f32 v[108:109], v[98:99], v[58:59], v[62:63]
	v_mov_b32_e32 v98, v136
	v_mov_b32_e32 v99, v82
	v_mov_b32_e32 v84, v117
	v_mov_b32_e32 v68, v75
	v_exp_f32_e32 v65, v65
	v_pk_fma_f32 v[108:109], v[98:99], v[102:103], v[108:109]
	v_mov_b32_e32 v102, v132
	v_mov_b32_e32 v103, v80
	v_mov_b32_dpp v116, v61 row_ror:2 row_mask:0xf bank_mask:0xf
	v_cndmask_b32_e64 v100, v141, v142, s[8:9]
	v_pk_fma_f32 v[60:61], v[60:61], v[84:85], v[68:69]
	v_mov_b32_e32 v82, v137
	v_pk_fma_f32 v[106:107], v[102:103], v[106:107], v[108:109]
	v_cndmask_b32_e64 v109, v116, v64, s[6:7]
	v_cndmask_b32_e64 v108, v143, v144, s[6:7]
	v_pk_fma_f32 v[60:61], v[82:83], v[100:101], v[60:61]
	v_mov_b32_e32 v80, v133
	v_pk_fma_f32 v[60:61], v[80:81], v[108:109], v[60:61]
	v_add_f32_e32 v65, 1.0, v65
	v_mul_f32_e32 v75, 0xbfb8aa3b, v106
	v_mul_f32_e32 v100, 0xbfb8aa3b, v60
	v_mul_f32_e32 v64, 0xbfb8aa3b, v104
	v_rcp_f32_e32 v65, v65
	v_exp_f32_e32 v75, v75
	v_exp_f32_e32 v100, v100
	v_exp_f32_e32 v64, v64
	v_mul_f32_e32 v65, v72, v65
	v_add_f32_e32 v72, 1.0, v75
	v_add_f32_e32 v75, 1.0, v100
	v_add_f32_e32 v64, 1.0, v64
	v_rcp_f32_e32 v72, v72
	v_rcp_f32_e32 v75, v75
	v_rcp_f32_e32 v64, v64
	v_mul_f32_e32 v72, v106, v72
	v_mul_f32_e32 v60, v60, v75
	v_mul_f32_e32 v64, v104, v64
	v_mul_f32_e32 v72, v72, v107
	v_mul_f32_e32 v61, v60, v61
	v_mul_f32_e32 v64, v64, v105
	v_mul_f32_e32 v65, v65, v73
	v_cvt_pk_bf16_f32 v60, v64, v65
	v_cvt_pk_bf16_f32 v61, v72, v61
	v_mov_b32_dpp v75, v54 row_ror:1 row_mask:0xf bank_mask:0xf
	v_mov_b32_dpp v109, v50 row_ror:1 row_mask:0xf bank_mask:0xf
	v_mov_b32_e32 v72, v54
	v_mov_b32_e32 v73, v50
	global_store_dwordx2 v[122:123], v[60:61], off offset:8
	v_mov_b32_dpp v100, v54 row_ror:2 row_mask:0xf bank_mask:0xf
	v_mov_b32_dpp v117, v50 row_ror:2 row_mask:0xf bank_mask:0xf
	v_cndmask_b32_e64 v61, v109, v145, s[8:9]
	v_cndmask_b32_e64 v60, v75, v71, s[8:9]
	v_pk_fma_f32 v[72:73], v[72:73], v[76:77], v[78:79]
	v_mov_b32_dpp v101, v55 row_ror:1 row_mask:0xf bank_mask:0xf
	v_cndmask_b32_e64 v65, v117, v146, s[6:7]
	v_cndmask_b32_e64 v64, v100, v110, s[6:7]
	v_pk_fma_f32 v[60:61], v[92:93], v[60:61], v[72:73]
	v_mov_b32_dpp v71, v51 row_ror:1 row_mask:0xf bank_mask:0xf
	v_mov_b32_e32 v50, v55
	v_mov_b32_dpp v104, v55 row_ror:2 row_mask:0xf bank_mask:0xf
	v_pk_fma_f32 v[60:61], v[94:95], v[64:65], v[60:61]
	v_mov_b32_dpp v110, v51 row_ror:2 row_mask:0xf bank_mask:0xf
	v_cndmask_b32_e64 v65, v71, v114, s[8:9]
	v_cndmask_b32_e64 v64, v101, v111, s[8:9]
	v_pk_fma_f32 v[50:51], v[50:51], v[90:91], v[66:67]
	v_cndmask_b32_e64 v73, v110, v134, s[6:7]
	v_cndmask_b32_e64 v72, v104, v112, s[6:7]
	v_pk_fma_f32 v[50:51], v[88:89], v[64:65], v[50:51]
	v_mov_b32_dpp v105, v56 row_ror:1 row_mask:0xf bank_mask:0xf
	v_pk_fma_f32 v[50:51], v[86:87], v[72:73], v[50:51]
	v_mov_b32_dpp v111, v52 row_ror:1 row_mask:0xf bank_mask:0xf
	v_mov_b32_e32 v72, v56
	v_mov_b32_e32 v73, v52
	v_mov_b32_dpp v106, v56 row_ror:2 row_mask:0xf bank_mask:0xf
	v_mov_b32_dpp v112, v52 row_ror:2 row_mask:0xf bank_mask:0xf
	v_cndmask_b32_e64 v55, v111, v115, s[8:9]
	v_cndmask_b32_e64 v54, v105, v113, s[8:9]
	v_pk_fma_f32 v[72:73], v[72:73], v[58:59], v[62:63]
	v_cndmask_b32_e64 v65, v112, v135, s[6:7]
	v_cndmask_b32_e64 v64, v106, v140, s[6:7]
	v_pk_fma_f32 v[54:55], v[98:99], v[54:55], v[72:73]
	v_mov_b32_dpp v56, v53 row_ror:1 row_mask:0xf bank_mask:0xf
	v_mul_f32_e32 v52, 0xbfb8aa3b, v60
	v_pk_fma_f32 v[54:55], v[102:103], v[64:65], v[54:55]
	v_cndmask_b32_e64 v65, v56, v74, s[8:9]
	v_exp_f32_e32 v74, v52
	v_mov_b32_dpp v107, v57 row_ror:1 row_mask:0xf bank_mask:0xf
	v_mov_b32_e32 v52, v57
	v_mov_b32_dpp v108, v57 row_ror:2 row_mask:0xf bank_mask:0xf
	v_mov_b32_dpp v113, v53 row_ror:2 row_mask:0xf bank_mask:0xf
	v_cndmask_b32_e64 v64, v107, v141, s[8:9]
	v_pk_fma_f32 v[52:53], v[52:53], v[84:85], v[68:69]
	v_add_f32_e32 v57, 1.0, v74
	v_pk_fma_f32 v[52:53], v[82:83], v[64:65], v[52:53]
	v_rcp_f32_e32 v57, v57
	v_mul_f32_e32 v64, 0xbfb8aa3b, v50
	v_exp_f32_e32 v64, v64
	v_cndmask_b32_e64 v73, v113, v116, s[6:7]
	v_cndmask_b32_e64 v72, v108, v143, s[6:7]
	v_mul_f32_e32 v57, v60, v57
	v_pk_fma_f32 v[52:53], v[80:81], v[72:73], v[52:53]
	v_mul_f32_e32 v57, v57, v61
	v_add_f32_e32 v60, 1.0, v64
	v_mul_f32_e32 v61, 0xbfb8aa3b, v54
	v_rcp_f32_e32 v60, v60
	v_exp_f32_e32 v61, v61
	v_mul_f32_e32 v64, 0xbfb8aa3b, v52
	v_exp_f32_e32 v64, v64
	v_mul_f32_e32 v50, v50, v60
	v_add_f32_e32 v60, 1.0, v61
	v_rcp_f32_e32 v60, v60
	v_add_f32_e32 v61, 1.0, v64
	v_rcp_f32_e32 v61, v61
	v_mul_f32_e32 v50, v50, v51
	v_mul_f32_e32 v51, v54, v60
	v_mul_f32_e32 v51, v51, v55
	v_mul_f32_e32 v52, v52, v61
	v_cvt_pk_bf16_f32 v50, v57, v50
	v_mul_f32_e32 v52, v52, v53
	v_cvt_pk_bf16_f32 v51, v51, v52
	v_mov_b32_dpp v57, v46 row_ror:1 row_mask:0xf bank_mask:0xf
	v_mov_b32_dpp v114, v42 row_ror:1 row_mask:0xf bank_mask:0xf
	v_mov_b32_e32 v54, v46
	v_mov_b32_e32 v55, v42
	global_store_dwordx2 v[118:119], v[50:51], off offset:8
	v_mov_b32_dpp v60, v46 row_ror:2 row_mask:0xf bank_mask:0xf
	v_mov_b32_dpp v115, v42 row_ror:2 row_mask:0xf bank_mask:0xf
	v_cndmask_b32_e64 v51, v114, v109, s[8:9]
	v_cndmask_b32_e64 v50, v57, v75, s[8:9]
	v_pk_fma_f32 v[54:55], v[54:55], v[76:77], v[78:79]
	v_mov_b32_dpp v61, v47 row_ror:1 row_mask:0xf bank_mask:0xf
	v_cndmask_b32_e64 v53, v115, v117, s[6:7]
	v_cndmask_b32_e64 v52, v60, v100, s[6:7]
	v_pk_fma_f32 v[50:51], v[92:93], v[50:51], v[54:55]
	v_mov_b32_dpp v75, v43 row_ror:1 row_mask:0xf bank_mask:0xf
	v_mov_b32_e32 v42, v47
	v_mov_b32_dpp v64, v47 row_ror:2 row_mask:0xf bank_mask:0xf
	v_pk_fma_f32 v[50:51], v[94:95], v[52:53], v[50:51]
	v_mov_b32_dpp v100, v43 row_ror:2 row_mask:0xf bank_mask:0xf
	v_cndmask_b32_e64 v53, v75, v71, s[8:9]
	v_cndmask_b32_e64 v52, v61, v101, s[8:9]
	v_pk_fma_f32 v[42:43], v[42:43], v[90:91], v[66:67]
	v_cndmask_b32_e64 v55, v100, v110, s[6:7]
	v_cndmask_b32_e64 v54, v64, v104, s[6:7]
	v_pk_fma_f32 v[42:43], v[88:89], v[52:53], v[42:43]
	v_mov_b32_dpp v65, v48 row_ror:1 row_mask:0xf bank_mask:0xf
	v_pk_fma_f32 v[42:43], v[86:87], v[54:55], v[42:43]
	v_mov_b32_dpp v71, v44 row_ror:1 row_mask:0xf bank_mask:0xf
	v_mov_b32_e32 v54, v48
	v_mov_b32_e32 v55, v44
	v_mov_b32_dpp v72, v48 row_ror:2 row_mask:0xf bank_mask:0xf
	v_mov_b32_dpp v101, v44 row_ror:2 row_mask:0xf bank_mask:0xf
	v_cndmask_b32_e64 v47, v71, v111, s[8:9]
	v_cndmask_b32_e64 v46, v65, v105, s[8:9]
	v_pk_fma_f32 v[54:55], v[54:55], v[58:59], v[62:63]
	v_cndmask_b32_e64 v53, v101, v112, s[6:7]
	v_cndmask_b32_e64 v52, v72, v106, s[6:7]
	v_pk_fma_f32 v[46:47], v[98:99], v[46:47], v[54:55]
	v_mov_b32_dpp v48, v45 row_ror:1 row_mask:0xf bank_mask:0xf
	v_mul_f32_e32 v44, 0xbfb8aa3b, v50
	v_pk_fma_f32 v[46:47], v[102:103], v[52:53], v[46:47]
	v_cndmask_b32_e64 v53, v48, v56, s[8:9]
	v_exp_f32_e32 v56, v44
	v_mov_b32_dpp v73, v49 row_ror:1 row_mask:0xf bank_mask:0xf
	v_mov_b32_e32 v44, v49
	v_mov_b32_dpp v74, v49 row_ror:2 row_mask:0xf bank_mask:0xf
	v_mov_b32_dpp v104, v45 row_ror:2 row_mask:0xf bank_mask:0xf
	v_cndmask_b32_e64 v52, v73, v107, s[8:9]
	v_pk_fma_f32 v[44:45], v[44:45], v[84:85], v[68:69]
	v_add_f32_e32 v49, 1.0, v56
	v_pk_fma_f32 v[44:45], v[82:83], v[52:53], v[44:45]
	v_rcp_f32_e32 v49, v49
	v_mul_f32_e32 v52, 0xbfb8aa3b, v42
	v_exp_f32_e32 v52, v52
	v_cndmask_b32_e64 v55, v104, v113, s[6:7]
	v_cndmask_b32_e64 v54, v74, v108, s[6:7]
	v_mul_f32_e32 v49, v50, v49
	v_pk_fma_f32 v[44:45], v[80:81], v[54:55], v[44:45]
	v_mul_f32_e32 v49, v49, v51
	v_add_f32_e32 v50, 1.0, v52
	v_mul_f32_e32 v51, 0xbfb8aa3b, v46
	v_rcp_f32_e32 v50, v50
	v_exp_f32_e32 v51, v51
	v_mul_f32_e32 v52, 0xbfb8aa3b, v44
	v_exp_f32_e32 v52, v52
	v_mul_f32_e32 v42, v42, v50
	v_add_f32_e32 v50, 1.0, v51
	v_rcp_f32_e32 v50, v50
	v_add_f32_e32 v51, 1.0, v52
	v_rcp_f32_e32 v51, v51
	v_mul_f32_e32 v42, v42, v43
	v_mul_f32_e32 v43, v46, v50
	v_mul_f32_e32 v43, v43, v47
	v_mul_f32_e32 v44, v44, v51
	v_mul_f32_e32 v44, v44, v45
	v_cvt_pk_bf16_f32 v42, v49, v42
	v_cvt_pk_bf16_f32 v43, v43, v44
	global_store_dwordx2 v[120:121], v[42:43], off offset:8
	v_mov_b32_dpp v42, v38 row_ror:1 row_mask:0xf bank_mask:0xf
	v_mov_b32_dpp v43, v34 row_ror:1 row_mask:0xf bank_mask:0xf
	v_mov_b32_e32 v46, v38
	v_mov_b32_e32 v47, v34
	v_mov_b32_dpp v44, v38 row_ror:2 row_mask:0xf bank_mask:0xf
	v_mov_b32_dpp v45, v34 row_ror:2 row_mask:0xf bank_mask:0xf
	v_cndmask_b32_e64 v43, v43, v114, s[8:9]
	v_cndmask_b32_e64 v42, v42, v57, s[8:9]
	v_pk_fma_f32 v[46:47], v[46:47], v[76:77], v[78:79]
	v_cndmask_b32_e64 v45, v45, v115, s[6:7]
	v_cndmask_b32_e64 v44, v44, v60, s[6:7]
	v_pk_fma_f32 v[42:43], v[92:93], v[42:43], v[46:47]
	v_mov_b32_dpp v34, v35 row_ror:1 row_mask:0xf bank_mask:0xf
	v_mov_b32_dpp v49, v39 row_ror:1 row_mask:0xf bank_mask:0xf
	v_pk_fma_f32 v[42:43], v[94:95], v[44:45], v[42:43]
	v_cndmask_b32_e64 v45, v34, v75, s[8:9]
	v_mov_b32_e32 v34, v39
	v_mov_b32_dpp v50, v39 row_ror:2 row_mask:0xf bank_mask:0xf
	v_mov_b32_dpp v38, v35 row_ror:2 row_mask:0xf bank_mask:0xf
	v_cndmask_b32_e64 v44, v49, v61, s[8:9]
	v_pk_fma_f32 v[34:35], v[34:35], v[90:91], v[66:67]
	v_cndmask_b32_e64 v47, v38, v100, s[6:7]
	v_cndmask_b32_e64 v46, v50, v64, s[6:7]
	v_pk_fma_f32 v[34:35], v[88:89], v[44:45], v[34:35]
	v_mov_b32_dpp v51, v40 row_ror:1 row_mask:0xf bank_mask:0xf
	v_pk_fma_f32 v[34:35], v[86:87], v[46:47], v[34:35]
	v_mov_b32_dpp v38, v36 row_ror:1 row_mask:0xf bank_mask:0xf
	v_mov_b32_e32 v46, v40
	v_mov_b32_e32 v47, v36
	v_mov_b32_dpp v52, v40 row_ror:2 row_mask:0xf bank_mask:0xf
	v_mov_b32_dpp v44, v36 row_ror:2 row_mask:0xf bank_mask:0xf
	v_cndmask_b32_e64 v39, v38, v71, s[8:9]
	v_cndmask_b32_e64 v38, v51, v65, s[8:9]
	v_pk_fma_f32 v[46:47], v[46:47], v[58:59], v[62:63]
	v_cndmask_b32_e64 v45, v44, v101, s[6:7]
	v_cndmask_b32_e64 v44, v52, v72, s[6:7]
	v_pk_fma_f32 v[38:39], v[98:99], v[38:39], v[46:47]
	v_mov_b32_dpp v36, v37 row_ror:1 row_mask:0xf bank_mask:0xf
	v_pk_fma_f32 v[38:39], v[102:103], v[44:45], v[38:39]
	v_cndmask_b32_e64 v45, v36, v48, s[8:9]
	v_mov_b32_dpp v40, v37 row_ror:2 row_mask:0xf bank_mask:0xf
	v_mul_f32_e32 v36, 0xbfb8aa3b, v42
	v_cndmask_b32_e64 v47, v40, v104, s[6:7]
	v_exp_f32_e32 v40, v36
	v_mov_b32_e32 v36, v41
	v_mov_b32_dpp v53, v41 row_ror:1 row_mask:0xf bank_mask:0xf
	v_mov_b32_dpp v54, v41 row_ror:2 row_mask:0xf bank_mask:0xf
	v_add_f32_e32 v40, 1.0, v40
	v_mul_f32_e32 v41, 0xbfb8aa3b, v34
	v_rcp_f32_e32 v40, v40
	v_exp_f32_e32 v41, v41
	v_cndmask_b32_e64 v44, v53, v73, s[8:9]
	v_pk_fma_f32 v[36:37], v[36:37], v[84:85], v[68:69]
	v_cndmask_b32_e64 v46, v54, v74, s[6:7]
	v_pk_fma_f32 v[36:37], v[82:83], v[44:45], v[36:37]
	v_mul_f32_e32 v40, v42, v40
	v_pk_fma_f32 v[36:37], v[80:81], v[46:47], v[36:37]
	v_add_f32_e32 v41, 1.0, v41
	v_mul_f32_e32 v42, 0xbfb8aa3b, v38
	v_mul_f32_e32 v40, v40, v43
	v_rcp_f32_e32 v41, v41
	v_exp_f32_e32 v42, v42
	v_mul_f32_e32 v43, 0xbfb8aa3b, v36
	v_exp_f32_e32 v43, v43
	v_mul_f32_e32 v34, v34, v41
	v_add_f32_e32 v41, 1.0, v42
	v_rcp_f32_e32 v41, v41
	v_add_f32_e32 v42, 1.0, v43
	v_rcp_f32_e32 v42, v42
	v_mul_f32_e32 v34, v34, v35
	v_mul_f32_e32 v35, v38, v41
	v_mul_f32_e32 v35, v35, v39
	v_mul_f32_e32 v36, v36, v42
	v_mul_f32_e32 v36, v36, v37
	v_cvt_pk_bf16_f32 v34, v40, v34
	v_cvt_pk_bf16_f32 v35, v35, v36
	global_store_dwordx2 v[124:125], v[34:35], off offset:8
	v_mov_b32_e32 v70, 0
	v_mov_b32_e32 v34, 0
	v_mov_b32_e32 v35, 0
	v_mov_b32_e32 v36, 0
	v_mov_b32_e32 v37, 0
	s_and_saveexec_b64 s[38:39], s[4:5]
	ds_read_b128 v[34:37], v218
	s_or_b64 exec, exec, s[38:39]
	v_mov_b32_e32 v71, 0
	v_mov_b32_e32 v72, 0
	v_mov_b32_e32 v73, 0
	s_and_saveexec_b64 s[38:39], s[4:5]
	ds_read_b128 v[70:73], v218 offset:512
	s_or_b64 exec, exec, s[38:39]
	s_waitcnt lgkmcnt(0)
	v_mov_b32_dpp v50, v36 row_ror:1 row_mask:0xf bank_mask:0xf
	v_mov_b32_dpp v52, v36 row_ror:2 row_mask:0xf bank_mask:0xf
	v_mov_b32_dpp v42, v30 row_ror:1 row_mask:0xf bank_mask:0xf
	v_mov_b32_dpp v40, v34 row_ror:1 row_mask:0xf bank_mask:0xf
	v_mov_b32_e32 v38, v30
	v_mov_b32_e32 v39, v26
	v_mov_b32_dpp v57, v26 row_ror:1 row_mask:0xf bank_mask:0xf
	v_mov_b32_dpp v36, v70 row_ror:1 row_mask:0xf bank_mask:0xf
	v_mov_b32_dpp v60, v26 row_ror:2 row_mask:0xf bank_mask:0xf
	v_mov_b32_dpp v43, v30 row_ror:2 row_mask:0xf bank_mask:0xf
	v_mov_b32_dpp v44, v34 row_ror:2 row_mask:0xf bank_mask:0xf
	v_mov_b32_dpp v54, v37 row_ror:1 row_mask:0xf bank_mask:0xf
	v_mov_b32_dpp v56, v37 row_ror:2 row_mask:0xf bank_mask:0xf
	v_mov_b32_dpp v26, v70 row_ror:2 row_mask:0xf bank_mask:0xf
	v_cndmask_b32_e64 v37, v57, v36, s[8:9]
	v_cndmask_b32_e64 v36, v42, v40, s[8:9]
	v_pk_fma_f32 v[38:39], v[38:39], v[76:77], v[78:79]
	v_cndmask_b32_e64 v41, v60, v26, s[6:7]
	v_cndmask_b32_e64 v40, v43, v44, s[6:7]
	v_pk_fma_f32 v[36:37], v[92:93], v[36:37], v[38:39]
	v_pk_fma_f32 v[36:37], v[94:95], v[40:41], v[36:37]
	v_mov_b32_dpp v45, v31 row_ror:1 row_mask:0xf bank_mask:0xf
	v_mov_b32_dpp v46, v35 row_ror:1 row_mask:0xf bank_mask:0xf
	v_mov_b32_dpp v47, v31 row_ror:2 row_mask:0xf bank_mask:0xf
	v_mov_b32_e32 v30, v31
	v_mov_b32_e32 v31, v27
	v_mov_b32_dpp v40, v27 row_ror:1 row_mask:0xf bank_mask:0xf
	v_mov_b32_dpp v26, v71 row_ror:1 row_mask:0xf bank_mask:0xf
	v_pk_fma_f32 v[30:31], v[30:31], v[90:91], v[66:67]
	v_mov_b32_dpp v41, v27 row_ror:2 row_mask:0xf bank_mask:0xf
	v_cndmask_b32_e64 v27, v40, v26, s[8:9]
	v_cndmask_b32_e64 v26, v45, v46, s[8:9]
	v_pk_fma_f32 v[26:27], v[88:89], v[26:27], v[30:31]
	v_mov_b32_dpp v48, v35 row_ror:2 row_mask:0xf bank_mask:0xf
	v_mov_b32_dpp v49, v32 row_ror:1 row_mask:0xf bank_mask:0xf
	v_mov_b32_e32 v34, v32
	v_mov_b32_e32 v35, v28
	v_mov_b32_dpp v38, v71 row_ror:2 row_mask:0xf bank_mask:0xf
	v_mov_b32_dpp v44, v28 row_ror:1 row_mask:0xf bank_mask:0xf
	v_mov_b32_dpp v30, v72 row_ror:1 row_mask:0xf bank_mask:0xf
	v_mov_b32_dpp v46, v28 row_ror:2 row_mask:0xf bank_mask:0xf
	v_mov_b32_dpp v51, v32 row_ror:2 row_mask:0xf bank_mask:0xf
	v_cndmask_b32_e64 v39, v41, v38, s[6:7]
	v_cndmask_b32_e64 v38, v47, v48, s[6:7]
	v_mov_b32_dpp v28, v72 row_ror:2 row_mask:0xf bank_mask:0xf
	v_cndmask_b32_e64 v31, v44, v30, s[8:9]
	v_cndmask_b32_e64 v30, v49, v50, s[8:9]
	v_pk_fma_f32 v[34:35], v[34:35], v[58:59], v[62:63]
	v_pk_fma_f32 v[26:27], v[86:87], v[38:39], v[26:27]
	v_cndmask_b32_e64 v39, v46, v28, s[6:7]
	v_cndmask_b32_e64 v38, v51, v52, s[6:7]
	v_pk_fma_f32 v[30:31], v[98:99], v[30:31], v[34:35]
	v_pk_fma_f32 v[30:31], v[102:103], v[38:39], v[30:31]
	v_mov_b32_dpp v53, v33 row_ror:1 row_mask:0xf bank_mask:0xf
	v_mov_b32_dpp v55, v33 row_ror:2 row_mask:0xf bank_mask:0xf
	v_mov_b32_e32 v32, v33
	v_mov_b32_e32 v33, v29
	v_mov_b32_dpp v38, v29 row_ror:1 row_mask:0xf bank_mask:0xf
	v_mov_b32_dpp v28, v73 row_ror:1 row_mask:0xf bank_mask:0xf
	v_pk_fma_f32 v[32:33], v[32:33], v[84:85], v[68:69]
	v_mov_b32_dpp v39, v29 row_ror:2 row_mask:0xf bank_mask:0xf
	v_cndmask_b32_e64 v29, v38, v28, s[8:9]
	v_cndmask_b32_e64 v28, v53, v54, s[8:9]
	v_pk_fma_f32 v[28:29], v[82:83], v[28:29], v[32:33]
	v_mul_f32_e32 v33, 0xbfb8aa3b, v26
	v_exp_f32_e32 v33, v33
	v_mov_b32_dpp v34, v73 row_ror:2 row_mask:0xf bank_mask:0xf
	v_cndmask_b32_e64 v35, v39, v34, s[6:7]
	v_mul_f32_e32 v34, 0xbfb8aa3b, v36
	v_exp_f32_e32 v48, v34
	v_cndmask_b32_e64 v34, v55, v56, s[6:7]
	v_pk_fma_f32 v[28:29], v[80:81], v[34:35], v[28:29]
	v_add_f32_e32 v33, 1.0, v33
	v_mul_f32_e32 v34, 0xbfb8aa3b, v30
	v_rcp_f32_e32 v33, v33
	v_exp_f32_e32 v34, v34
	v_mul_f32_e32 v35, 0xbfb8aa3b, v28
	v_exp_f32_e32 v35, v35
	v_mul_f32_e32 v26, v26, v33
	v_add_f32_e32 v33, 1.0, v34
	v_add_f32_e32 v32, 1.0, v48
	v_rcp_f32_e32 v33, v33
	v_add_f32_e32 v34, 1.0, v35
	v_rcp_f32_e32 v32, v32
	v_rcp_f32_e32 v34, v34
	v_mul_f32_e32 v26, v26, v27
	v_mul_f32_e32 v27, v30, v33
	v_mul_f32_e32 v32, v36, v32
	v_mul_f32_e32 v27, v27, v31
	v_mul_f32_e32 v28, v28, v34
	v_mul_f32_e32 v32, v32, v37
	v_mul_f32_e32 v28, v28, v29
	v_cvt_pk_bf16_f32 v26, v32, v26
	v_cvt_pk_bf16_f32 v27, v27, v28
	global_store_dwordx2 v[96:97], v[26:27], off offset:8
	v_mov_b32_dpp v34, v22 row_ror:1 row_mask:0xf bank_mask:0xf
	v_mov_b32_e32 v26, v22
	v_mov_b32_e32 v27, v18
	v_mov_b32_dpp v56, v18 row_ror:1 row_mask:0xf bank_mask:0xf
	v_mov_b32_dpp v35, v22 row_ror:2 row_mask:0xf bank_mask:0xf
	v_cndmask_b32_e64 v31, v56, v57, s[8:9]
	v_mov_b32_dpp v61, v18 row_ror:2 row_mask:0xf bank_mask:0xf
	v_cndmask_b32_e64 v30, v34, v42, s[8:9]
	v_pk_fma_f32 v[26:27], v[26:27], v[76:77], v[78:79]
	v_cndmask_b32_e64 v33, v61, v60, s[6:7]
	v_cndmask_b32_e64 v32, v35, v43, s[6:7]
	v_pk_fma_f32 v[26:27], v[92:93], v[30:31], v[26:27]
	v_pk_fma_f32 v[26:27], v[94:95], v[32:33], v[26:27]
	v_mov_b32_dpp v32, v19 row_ror:1 row_mask:0xf bank_mask:0xf
	v_mov_b32_dpp v36, v23 row_ror:1 row_mask:0xf bank_mask:0xf
	v_mov_b32_dpp v37, v23 row_ror:2 row_mask:0xf bank_mask:0xf
	v_mov_b32_e32 v22, v23
	v_mov_b32_e32 v23, v19
	v_mov_b32_dpp v33, v19 row_ror:2 row_mask:0xf bank_mask:0xf
	v_cndmask_b32_e64 v19, v32, v40, s[8:9]
	v_mov_b32_dpp v48, v24 row_ror:1 row_mask:0xf bank_mask:0xf
	v_mov_b32_e32 v28, v24
	v_mov_b32_e32 v29, v20
	v_cndmask_b32_e64 v18, v36, v45, s[8:9]
	v_cndmask_b32_e64 v31, v33, v41, s[6:7]
	v_pk_fma_f32 v[22:23], v[22:23], v[90:91], v[66:67]
	v_mov_b32_dpp v40, v20 row_ror:1 row_mask:0xf bank_mask:0xf
	v_mov_b32_dpp v50, v24 row_ror:2 row_mask:0xf bank_mask:0xf
	v_cndmask_b32_e64 v30, v37, v47, s[6:7]
	v_pk_fma_f32 v[18:19], v[88:89], v[18:19], v[22:23]
	v_mov_b32_dpp v41, v20 row_ror:2 row_mask:0xf bank_mask:0xf
	v_cndmask_b32_e64 v23, v40, v44, s[8:9]
	v_cndmask_b32_e64 v22, v48, v49, s[8:9]
	v_pk_fma_f32 v[28:29], v[28:29], v[58:59], v[62:63]
	v_pk_fma_f32 v[18:19], v[86:87], v[30:31], v[18:19]
	v_cndmask_b32_e64 v31, v41, v46, s[6:7]
	v_cndmask_b32_e64 v30, v50, v51, s[6:7]
	v_pk_fma_f32 v[22:23], v[98:99], v[22:23], v[28:29]
	v_pk_fma_f32 v[22:23], v[102:103], v[30:31], v[22:23]
	v_mov_b32_dpp v30, v21 row_ror:1 row_mask:0xf bank_mask:0xf
	v_mul_f32_e32 v28, 0xbfb8aa3b, v26
	v_mov_b32_dpp v52, v25 row_ror:1 row_mask:0xf bank_mask:0xf
	v_mov_b32_dpp v54, v25 row_ror:2 row_mask:0xf bank_mask:0xf
	v_mov_b32_e32 v24, v25
	v_mov_b32_e32 v25, v21
	v_mov_b32_dpp v31, v21 row_ror:2 row_mask:0xf bank_mask:0xf
	v_cndmask_b32_e64 v21, v30, v38, s[8:9]
	v_exp_f32_e32 v38, v28
	v_cndmask_b32_e64 v20, v52, v53, s[8:9]
	v_pk_fma_f32 v[24:25], v[24:25], v[84:85], v[68:69]
	v_cndmask_b32_e64 v29, v31, v39, s[6:7]
	v_pk_fma_f32 v[20:21], v[82:83], v[20:21], v[24:25]
	v_add_f32_e32 v24, 1.0, v38
	v_mul_f32_e32 v25, 0xbfb8aa3b, v18
	v_rcp_f32_e32 v24, v24
	v_exp_f32_e32 v25, v25
	v_cndmask_b32_e64 v28, v54, v55, s[6:7]
	v_pk_fma_f32 v[20:21], v[80:81], v[28:29], v[20:21]
	v_mul_f32_e32 v24, v26, v24
	v_add_f32_e32 v25, 1.0, v25
	v_mul_f32_e32 v26, 0xbfb8aa3b, v22
	v_mul_f32_e32 v24, v24, v27
	v_rcp_f32_e32 v25, v25
	v_exp_f32_e32 v26, v26
	v_mul_f32_e32 v27, 0xbfb8aa3b, v20
	v_exp_f32_e32 v27, v27
	v_mul_f32_e32 v18, v18, v25
	v_add_f32_e32 v25, 1.0, v26
	v_rcp_f32_e32 v25, v25
	v_add_f32_e32 v26, 1.0, v27
	v_rcp_f32_e32 v26, v26
	v_mul_f32_e32 v18, v18, v19
	v_mul_f32_e32 v19, v22, v25
	v_mul_f32_e32 v19, v19, v23
	v_mul_f32_e32 v20, v20, v26
	v_mul_f32_e32 v20, v20, v21
	v_cvt_pk_bf16_f32 v18, v24, v18
	v_cvt_pk_bf16_f32 v19, v19, v20
	global_store_dwordx2 v[126:127], v[18:19], off offset:8
	v_mov_b32_dpp v26, v14 row_ror:1 row_mask:0xf bank_mask:0xf
	v_mov_b32_e32 v18, v14
	v_mov_b32_e32 v19, v10
	v_mov_b32_dpp v44, v10 row_ror:1 row_mask:0xf bank_mask:0xf
	v_mov_b32_dpp v27, v14 row_ror:2 row_mask:0xf bank_mask:0xf
	v_cndmask_b32_e64 v23, v44, v56, s[8:9]
	v_mov_b32_dpp v45, v10 row_ror:2 row_mask:0xf bank_mask:0xf
	v_cndmask_b32_e64 v22, v26, v34, s[8:9]
	v_pk_fma_f32 v[18:19], v[18:19], v[76:77], v[78:79]
	v_cndmask_b32_e64 v25, v45, v61, s[6:7]
	v_cndmask_b32_e64 v24, v27, v35, s[6:7]
	v_pk_fma_f32 v[18:19], v[92:93], v[22:23], v[18:19]
	v_pk_fma_f32 v[18:19], v[94:95], v[24:25], v[18:19]
	v_mov_b32_dpp v24, v11 row_ror:1 row_mask:0xf bank_mask:0xf
	v_mov_b32_dpp v28, v15 row_ror:1 row_mask:0xf bank_mask:0xf
	v_mov_b32_dpp v29, v15 row_ror:2 row_mask:0xf bank_mask:0xf
	v_mov_b32_e32 v14, v15
	v_mov_b32_e32 v15, v11
	v_mov_b32_dpp v25, v11 row_ror:2 row_mask:0xf bank_mask:0xf
	v_cndmask_b32_e64 v11, v24, v32, s[8:9]
	v_mov_b32_dpp v38, v16 row_ror:1 row_mask:0xf bank_mask:0xf
	v_mov_b32_e32 v20, v16
	v_mov_b32_e32 v21, v12
	v_cndmask_b32_e64 v10, v28, v36, s[8:9]
	v_cndmask_b32_e64 v23, v25, v33, s[6:7]
	v_pk_fma_f32 v[14:15], v[14:15], v[90:91], v[66:67]
	v_mov_b32_dpp v32, v12 row_ror:1 row_mask:0xf bank_mask:0xf
	v_mov_b32_dpp v39, v16 row_ror:2 row_mask:0xf bank_mask:0xf
	v_cndmask_b32_e64 v22, v29, v37, s[6:7]
	v_pk_fma_f32 v[10:11], v[88:89], v[10:11], v[14:15]
	v_mov_b32_dpp v33, v12 row_ror:2 row_mask:0xf bank_mask:0xf
	v_cndmask_b32_e64 v15, v32, v40, s[8:9]
	v_cndmask_b32_e64 v14, v38, v48, s[8:9]
	v_pk_fma_f32 v[20:21], v[20:21], v[58:59], v[62:63]
	v_pk_fma_f32 v[10:11], v[86:87], v[22:23], v[10:11]
	v_cndmask_b32_e64 v23, v33, v41, s[6:7]
	v_cndmask_b32_e64 v22, v39, v50, s[6:7]
	v_pk_fma_f32 v[14:15], v[98:99], v[14:15], v[20:21]
	v_pk_fma_f32 v[14:15], v[102:103], v[22:23], v[14:15]
	v_mov_b32_dpp v22, v13 row_ror:1 row_mask:0xf bank_mask:0xf
	v_mul_f32_e32 v20, 0xbfb8aa3b, v18
	v_mov_b32_dpp v42, v17 row_ror:1 row_mask:0xf bank_mask:0xf
	v_mov_b32_dpp v43, v17 row_ror:2 row_mask:0xf bank_mask:0xf
	v_mov_b32_e32 v16, v17
	v_mov_b32_e32 v17, v13
	v_mov_b32_dpp v23, v13 row_ror:2 row_mask:0xf bank_mask:0xf
	v_cndmask_b32_e64 v13, v22, v30, s[8:9]
	v_exp_f32_e32 v30, v20
	v_cndmask_b32_e64 v12, v42, v52, s[8:9]
	v_pk_fma_f32 v[16:17], v[16:17], v[84:85], v[68:69]
	v_cndmask_b32_e64 v21, v23, v31, s[6:7]
	v_pk_fma_f32 v[12:13], v[82:83], v[12:13], v[16:17]
	v_add_f32_e32 v16, 1.0, v30
	v_mul_f32_e32 v17, 0xbfb8aa3b, v10
	v_rcp_f32_e32 v16, v16
	v_exp_f32_e32 v17, v17
	v_cndmask_b32_e64 v20, v43, v54, s[6:7]
	v_pk_fma_f32 v[12:13], v[80:81], v[20:21], v[12:13]
	v_mul_f32_e32 v16, v18, v16
	v_add_f32_e32 v17, 1.0, v17
	v_mul_f32_e32 v18, 0xbfb8aa3b, v14
	v_mul_f32_e32 v16, v16, v19
	v_rcp_f32_e32 v17, v17
	v_exp_f32_e32 v18, v18
	v_mul_f32_e32 v19, 0xbfb8aa3b, v12
	v_exp_f32_e32 v19, v19
	v_mul_f32_e32 v10, v10, v17
	v_add_f32_e32 v17, 1.0, v18
	v_rcp_f32_e32 v17, v17
	v_add_f32_e32 v18, 1.0, v19
	v_rcp_f32_e32 v18, v18
	v_mul_f32_e32 v10, v10, v11
	v_mul_f32_e32 v11, v14, v17
	v_mul_f32_e32 v11, v11, v15
	v_mul_f32_e32 v12, v12, v18
	v_mul_f32_e32 v12, v12, v13
	v_cvt_pk_bf16_f32 v10, v16, v10
	v_cvt_pk_bf16_f32 v11, v11, v12
	global_store_dwordx2 v[128:129], v[10:11], off offset:8
	v_mov_b32_dpp v14, v6 row_ror:1 row_mask:0xf bank_mask:0xf
	v_mov_b32_e32 v10, v6
	v_mov_b32_e32 v11, v2
	v_mov_b32_dpp v15, v2 row_ror:1 row_mask:0xf bank_mask:0xf
	v_mov_b32_dpp v17, v2 row_ror:2 row_mask:0xf bank_mask:0xf
	v_cndmask_b32_e64 v15, v15, v44, s[8:9]
	v_cndmask_b32_e64 v14, v14, v26, s[8:9]
	v_pk_fma_f32 v[10:11], v[10:11], v[76:77], v[78:79]
	v_mov_b32_dpp v16, v6 row_ror:2 row_mask:0xf bank_mask:0xf
	v_mov_b32_dpp v18, v7 row_ror:1 row_mask:0xf bank_mask:0xf
	v_mov_b32_dpp v19, v7 row_ror:2 row_mask:0xf bank_mask:0xf
	v_mov_b32_e32 v6, v7
	v_mov_b32_e32 v7, v3
	v_pk_fma_f32 v[10:11], v[92:93], v[14:15], v[10:11]
	v_mov_b32_dpp v2, v3 row_ror:1 row_mask:0xf bank_mask:0xf
	v_pk_fma_f32 v[6:7], v[6:7], v[90:91], v[66:67]
	v_mov_b32_dpp v14, v3 row_ror:2 row_mask:0xf bank_mask:0xf
	v_cndmask_b32_e64 v3, v2, v24, s[8:9]
	v_cndmask_b32_e64 v2, v18, v28, s[8:9]
	v_pk_fma_f32 v[2:3], v[88:89], v[2:3], v[6:7]
	v_mov_b32_dpp v20, v8 row_ror:1 row_mask:0xf bank_mask:0xf
	v_mov_b32_e32 v12, v8
	v_mov_b32_e32 v13, v4
	v_mov_b32_dpp v6, v4 row_ror:1 row_mask:0xf bank_mask:0xf
	v_cndmask_b32_e64 v15, v14, v25, s[6:7]
	v_cndmask_b32_e64 v14, v19, v29, s[6:7]
	v_cndmask_b32_e64 v7, v6, v32, s[8:9]
	v_cndmask_b32_e64 v6, v20, v38, s[8:9]
	v_pk_fma_f32 v[12:13], v[12:13], v[58:59], v[62:63]
	v_cndmask_b32_e64 v17, v17, v45, s[6:7]
	v_cndmask_b32_e64 v16, v16, v27, s[6:7]
	v_pk_fma_f32 v[2:3], v[86:87], v[14:15], v[2:3]
	v_pk_fma_f32 v[6:7], v[98:99], v[6:7], v[12:13]
	v_mov_b32_dpp v21, v8 row_ror:2 row_mask:0xf bank_mask:0xf
	v_pk_fma_f32 v[10:11], v[94:95], v[16:17], v[10:11]
	v_mov_b32_dpp v14, v4 row_ror:2 row_mask:0xf bank_mask:0xf
	v_mov_b32_dpp v12, v5 row_ror:2 row_mask:0xf bank_mask:0xf
	v_cndmask_b32_e64 v15, v14, v33, s[6:7]
	v_cndmask_b32_e64 v14, v21, v39, s[6:7]
	v_cndmask_b32_e64 v13, v12, v23, s[6:7]
	v_mul_f32_e32 v12, 0xbfb8aa3b, v10
	v_pk_fma_f32 v[6:7], v[102:103], v[14:15], v[6:7]
	v_exp_f32_e32 v14, v12
	v_mov_b32_dpp v30, v9 row_ror:1 row_mask:0xf bank_mask:0xf
	v_mov_b32_dpp v31, v9 row_ror:2 row_mask:0xf bank_mask:0xf
	v_mov_b32_e32 v8, v9
	v_mov_b32_e32 v9, v5
	v_mov_b32_dpp v4, v5 row_ror:1 row_mask:0xf bank_mask:0xf
	v_cndmask_b32_e64 v5, v4, v22, s[8:9]
	v_cndmask_b32_e64 v4, v30, v42, s[8:9]
	v_pk_fma_f32 v[8:9], v[8:9], v[84:85], v[68:69]
	v_cndmask_b32_e64 v12, v31, v43, s[6:7]
	v_pk_fma_f32 v[4:5], v[82:83], v[4:5], v[8:9]
	v_add_f32_e32 v8, 1.0, v14
	v_mul_f32_e32 v9, 0xbfb8aa3b, v2
	v_rcp_f32_e32 v8, v8
	v_exp_f32_e32 v9, v9
	v_pk_fma_f32 v[4:5], v[80:81], v[12:13], v[4:5]
	s_andn2_b64 vcc, exec, s[10:11]
	v_mul_f32_e32 v8, v10, v8
	v_add_f32_e32 v9, 1.0, v9
	v_mul_f32_e32 v10, 0xbfb8aa3b, v6
	v_mul_f32_e32 v8, v8, v11
	v_rcp_f32_e32 v9, v9
	v_exp_f32_e32 v10, v10
	v_mul_f32_e32 v11, 0xbfb8aa3b, v4
	v_exp_f32_e32 v11, v11
	v_mul_f32_e32 v2, v2, v9
	v_add_f32_e32 v9, 1.0, v10
	v_rcp_f32_e32 v9, v9
	v_add_f32_e32 v10, 1.0, v11
	v_rcp_f32_e32 v10, v10
	v_mul_f32_e32 v2, v2, v3
	v_mul_f32_e32 v3, v6, v9
	v_mul_f32_e32 v3, v3, v7
	v_mul_f32_e32 v4, v4, v10
	v_mul_f32_e32 v4, v4, v5
	v_cvt_pk_bf16_f32 v2, v8, v2
	v_cvt_pk_bf16_f32 v3, v3, v4
	global_store_dwordx2 v[130:131], v[2:3], off offset:8
	s_mov_b64 s[10:11], -1
	s_cbranch_vccnz .LBB0_1868
	s_andn2_b64 vcc, exec, s[0:1]
	s_cbranch_vccnz .LBB0_1867
	s_barrier
	s_branch .LBB0_1867
